# pre-epilogue realign barrier of the leading half moved behind the first epilogue loads (P4 P5 P6)
# speedup vs baseline: 1.0036x; 1.0036x over previous
.LBB0_469:
	v_lshl_add_u32 v146, s3, 8, v148
	v_lshl_or_b32 v144, s46, 8, v150
	v_lshlrev_b32_e32 v145, 1, v144
	v_lshl_add_u32 v228, v146, 11, v145
	v_add_u32_e32 v229, 0x8000, v228
	v_add_u32_e32 v230, 0x10000, v228
	v_add_u32_e32 v231, 0x18000, v228
	v_add_u32_e32 v232, 0x40000, v228
	v_add_u32_e32 v233, 0x48000, v228
	v_add_u32_e32 v234, 0x50000, v228
	v_add_u32_e32 v235, 0x58000, v228
	global_load_dwordx4 v[156:159], v228, s[20:21]
	global_load_dwordx4 v[160:163], v228, s[20:21] offset:256
	global_load_dwordx4 v[164:167], v229, s[20:21]
	global_load_dwordx4 v[168:171], v229, s[20:21] offset:256
	global_load_dwordx4 v[172:175], v230, s[20:21]
	global_load_dwordx4 v[176:179], v230, s[20:21] offset:256
	global_load_dwordx4 v[180:183], v231, s[20:21]
	global_load_dwordx4 v[184:187], v231, s[20:21] offset:256
	global_load_dwordx4 v[188:191], v232, s[20:21]
	global_load_dwordx4 v[192:195], v232, s[20:21] offset:256
	global_load_dwordx4 v[196:199], v233, s[20:21]
	global_load_dwordx4 v[200:203], v233, s[20:21] offset:256
	global_load_dwordx4 v[204:207], v234, s[20:21]
	global_load_dwordx4 v[208:211], v234, s[20:21] offset:256
	global_load_dwordx4 v[212:215], v235, s[20:21]
	global_load_dwordx4 v[224:227], v235, s[20:21] offset:256
	s_and_b64 vcc, exec, s[38:39]
	s_cbranch_vccz .Lp4ep_nobar
	s_barrier
.Lp4ep_nobar:
	s_waitcnt vmcnt(15)
	v_lshlrev_b32_e32 v244, 16, v156
	v_and_b32_e32 v245, 0xffff0000, v156
	v_lshlrev_b32_e32 v246, 16, v157
	v_and_b32_e32 v247, 0xffff0000, v157
	v_lshlrev_b32_e32 v250, 16, v158
	v_and_b32_e32 v251, 0xffff0000, v158
	v_lshlrev_b32_e32 v252, 16, v159
	v_and_b32_e32 v253, 0xffff0000, v159
	v_pk_add_f32 v[124:125], v[124:125], v[244:245]
	v_pk_add_f32 v[126:127], v[126:127], v[246:247]
	v_pk_add_f32 v[120:121], v[120:121], v[250:251]
	v_pk_add_f32 v[122:123], v[122:123], v[252:253]
	v_pk_mul_f32 v[254:255], v[124:125], v[124:125]
	v_pk_fma_f32 v[254:255], v[126:127], v[126:127], v[254:255]
	v_pk_fma_f32 v[254:255], v[120:121], v[120:121], v[254:255]
	v_pk_fma_f32 v[254:255], v[122:123], v[122:123], v[254:255]
	v_cvt_pk_bf16_f32 v124, v124, v125
	v_cvt_pk_bf16_f32 v125, v126, v127
	v_cvt_pk_bf16_f32 v126, v120, v121
	v_cvt_pk_bf16_f32 v127, v122, v123
	global_store_dwordx4 v228, v[124:127], s[20:21]
	s_waitcnt vmcnt(15)
	v_lshlrev_b32_e32 v244, 16, v160
	v_and_b32_e32 v245, 0xffff0000, v160
	v_lshlrev_b32_e32 v246, 16, v161
	v_and_b32_e32 v247, 0xffff0000, v161
	v_lshlrev_b32_e32 v250, 16, v162
	v_and_b32_e32 v251, 0xffff0000, v162
	v_lshlrev_b32_e32 v252, 16, v163
	v_and_b32_e32 v253, 0xffff0000, v163
	v_pk_add_f32 v[116:117], v[116:117], v[244:245]
	v_pk_add_f32 v[118:119], v[118:119], v[246:247]
	v_pk_add_f32 v[112:113], v[112:113], v[250:251]
	v_pk_add_f32 v[114:115], v[114:115], v[252:253]
	v_pk_fma_f32 v[254:255], v[116:117], v[116:117], v[254:255]
	v_pk_fma_f32 v[254:255], v[118:119], v[118:119], v[254:255]
	v_pk_fma_f32 v[254:255], v[112:113], v[112:113], v[254:255]
	v_pk_fma_f32 v[254:255], v[114:115], v[114:115], v[254:255]
	v_cvt_pk_bf16_f32 v116, v116, v117
	v_cvt_pk_bf16_f32 v117, v118, v119
	v_cvt_pk_bf16_f32 v118, v112, v113
	v_cvt_pk_bf16_f32 v119, v114, v115
	global_store_dwordx4 v228, v[116:119], s[20:21] offset:256
	v_add_f32_e32 v112, v254, v255
	s_waitcnt vmcnt(15)
	v_lshlrev_b32_e32 v244, 16, v164
	v_and_b32_e32 v245, 0xffff0000, v164
	v_lshlrev_b32_e32 v246, 16, v165
	v_and_b32_e32 v247, 0xffff0000, v165
	v_lshlrev_b32_e32 v250, 16, v166
	v_and_b32_e32 v251, 0xffff0000, v166
	v_lshlrev_b32_e32 v252, 16, v167
	v_and_b32_e32 v253, 0xffff0000, v167
	v_pk_add_f32 v[108:109], v[108:109], v[244:245]
	v_pk_add_f32 v[110:111], v[110:111], v[246:247]
	v_pk_add_f32 v[104:105], v[104:105], v[250:251]
	v_pk_add_f32 v[106:107], v[106:107], v[252:253]
	v_pk_mul_f32 v[254:255], v[108:109], v[108:109]
	v_pk_fma_f32 v[254:255], v[110:111], v[110:111], v[254:255]
	v_pk_fma_f32 v[254:255], v[104:105], v[104:105], v[254:255]
	v_pk_fma_f32 v[254:255], v[106:107], v[106:107], v[254:255]
	v_cvt_pk_bf16_f32 v108, v108, v109
	v_cvt_pk_bf16_f32 v109, v110, v111
	v_cvt_pk_bf16_f32 v110, v104, v105
	v_cvt_pk_bf16_f32 v111, v106, v107
	global_store_dwordx4 v229, v[108:111], s[20:21]
	s_waitcnt vmcnt(15)
	v_lshlrev_b32_e32 v244, 16, v168
	v_and_b32_e32 v245, 0xffff0000, v168
	v_lshlrev_b32_e32 v246, 16, v169
	v_and_b32_e32 v247, 0xffff0000, v169
	v_lshlrev_b32_e32 v250, 16, v170
	v_and_b32_e32 v251, 0xffff0000, v170
	v_lshlrev_b32_e32 v252, 16, v171
	v_and_b32_e32 v253, 0xffff0000, v171
	v_pk_add_f32 v[100:101], v[100:101], v[244:245]
	v_pk_add_f32 v[102:103], v[102:103], v[246:247]
	v_pk_add_f32 v[96:97], v[96:97], v[250:251]
	v_pk_add_f32 v[98:99], v[98:99], v[252:253]
	v_pk_fma_f32 v[254:255], v[100:101], v[100:101], v[254:255]
	v_pk_fma_f32 v[254:255], v[102:103], v[102:103], v[254:255]
	v_pk_fma_f32 v[254:255], v[96:97], v[96:97], v[254:255]
	v_pk_fma_f32 v[254:255], v[98:99], v[98:99], v[254:255]
	v_cvt_pk_bf16_f32 v100, v100, v101
	v_cvt_pk_bf16_f32 v101, v102, v103
	v_cvt_pk_bf16_f32 v102, v96, v97
	v_cvt_pk_bf16_f32 v103, v98, v99
	global_store_dwordx4 v229, v[100:103], s[20:21] offset:256
	v_add_f32_e32 v96, v254, v255
	s_waitcnt vmcnt(15)
	v_lshlrev_b32_e32 v244, 16, v172
	v_and_b32_e32 v245, 0xffff0000, v172
	v_lshlrev_b32_e32 v246, 16, v173
	v_and_b32_e32 v247, 0xffff0000, v173
	v_lshlrev_b32_e32 v250, 16, v174
	v_and_b32_e32 v251, 0xffff0000, v174
	v_lshlrev_b32_e32 v252, 16, v175
	v_and_b32_e32 v253, 0xffff0000, v175
	v_pk_add_f32 v[92:93], v[92:93], v[244:245]
	v_pk_add_f32 v[94:95], v[94:95], v[246:247]
	v_pk_add_f32 v[88:89], v[88:89], v[250:251]
	v_pk_add_f32 v[90:91], v[90:91], v[252:253]
	v_pk_mul_f32 v[254:255], v[92:93], v[92:93]
	v_pk_fma_f32 v[254:255], v[94:95], v[94:95], v[254:255]
	v_pk_fma_f32 v[254:255], v[88:89], v[88:89], v[254:255]
	v_pk_fma_f32 v[254:255], v[90:91], v[90:91], v[254:255]
	v_cvt_pk_bf16_f32 v92, v92, v93
	v_cvt_pk_bf16_f32 v93, v94, v95
	v_cvt_pk_bf16_f32 v94, v88, v89
	v_cvt_pk_bf16_f32 v95, v90, v91
	global_store_dwordx4 v230, v[92:95], s[20:21]
	s_waitcnt vmcnt(15)
	v_lshlrev_b32_e32 v244, 16, v176
	v_and_b32_e32 v245, 0xffff0000, v176
	v_lshlrev_b32_e32 v246, 16, v177
	v_and_b32_e32 v247, 0xffff0000, v177
	v_lshlrev_b32_e32 v250, 16, v178
	v_and_b32_e32 v251, 0xffff0000, v178
	v_lshlrev_b32_e32 v252, 16, v179
	v_and_b32_e32 v253, 0xffff0000, v179
	v_pk_add_f32 v[84:85], v[84:85], v[244:245]
	v_pk_add_f32 v[86:87], v[86:87], v[246:247]
	v_pk_add_f32 v[80:81], v[80:81], v[250:251]
	v_pk_add_f32 v[82:83], v[82:83], v[252:253]
	v_pk_fma_f32 v[254:255], v[84:85], v[84:85], v[254:255]
	v_pk_fma_f32 v[254:255], v[86:87], v[86:87], v[254:255]
	v_pk_fma_f32 v[254:255], v[80:81], v[80:81], v[254:255]
	v_pk_fma_f32 v[254:255], v[82:83], v[82:83], v[254:255]
	v_cvt_pk_bf16_f32 v84, v84, v85
	v_cvt_pk_bf16_f32 v85, v86, v87
	v_cvt_pk_bf16_f32 v86, v80, v81
	v_cvt_pk_bf16_f32 v87, v82, v83
	global_store_dwordx4 v230, v[84:87], s[20:21] offset:256
	v_add_f32_e32 v80, v254, v255
	s_waitcnt vmcnt(15)
	v_lshlrev_b32_e32 v244, 16, v180
	v_and_b32_e32 v245, 0xffff0000, v180
	v_lshlrev_b32_e32 v246, 16, v181
	v_and_b32_e32 v247, 0xffff0000, v181
	v_lshlrev_b32_e32 v250, 16, v182
	v_and_b32_e32 v251, 0xffff0000, v182
	v_lshlrev_b32_e32 v252, 16, v183
	v_and_b32_e32 v253, 0xffff0000, v183
	v_pk_add_f32 v[76:77], v[76:77], v[244:245]
	v_pk_add_f32 v[78:79], v[78:79], v[246:247]
	v_pk_add_f32 v[72:73], v[72:73], v[250:251]
	v_pk_add_f32 v[74:75], v[74:75], v[252:253]
	v_pk_mul_f32 v[254:255], v[76:77], v[76:77]
	v_pk_fma_f32 v[254:255], v[78:79], v[78:79], v[254:255]
	v_pk_fma_f32 v[254:255], v[72:73], v[72:73], v[254:255]
	v_pk_fma_f32 v[254:255], v[74:75], v[74:75], v[254:255]
	v_cvt_pk_bf16_f32 v76, v76, v77
	v_cvt_pk_bf16_f32 v77, v78, v79
	v_cvt_pk_bf16_f32 v78, v72, v73
	v_cvt_pk_bf16_f32 v79, v74, v75
	global_store_dwordx4 v231, v[76:79], s[20:21]
	s_waitcnt vmcnt(15)
	v_lshlrev_b32_e32 v244, 16, v184
	v_and_b32_e32 v245, 0xffff0000, v184
	v_lshlrev_b32_e32 v246, 16, v185
	v_and_b32_e32 v247, 0xffff0000, v185
	v_lshlrev_b32_e32 v250, 16, v186
	v_and_b32_e32 v251, 0xffff0000, v186
	v_lshlrev_b32_e32 v252, 16, v187
	v_and_b32_e32 v253, 0xffff0000, v187
	v_pk_add_f32 v[68:69], v[68:69], v[244:245]
	v_pk_add_f32 v[70:71], v[70:71], v[246:247]
	v_pk_add_f32 v[64:65], v[64:65], v[250:251]
	v_pk_add_f32 v[66:67], v[66:67], v[252:253]
	v_pk_fma_f32 v[254:255], v[68:69], v[68:69], v[254:255]
	v_pk_fma_f32 v[254:255], v[70:71], v[70:71], v[254:255]
	v_pk_fma_f32 v[254:255], v[64:65], v[64:65], v[254:255]
	v_pk_fma_f32 v[254:255], v[66:67], v[66:67], v[254:255]
	v_cvt_pk_bf16_f32 v68, v68, v69
	v_cvt_pk_bf16_f32 v69, v70, v71
	v_cvt_pk_bf16_f32 v70, v64, v65
	v_cvt_pk_bf16_f32 v71, v66, v67
	global_store_dwordx4 v231, v[68:71], s[20:21] offset:256
	v_add_f32_e32 v64, v254, v255
	s_waitcnt vmcnt(15)
	v_lshlrev_b32_e32 v244, 16, v188
	v_and_b32_e32 v245, 0xffff0000, v188
	v_lshlrev_b32_e32 v246, 16, v189
	v_and_b32_e32 v247, 0xffff0000, v189
	v_lshlrev_b32_e32 v250, 16, v190
	v_and_b32_e32 v251, 0xffff0000, v190
	v_lshlrev_b32_e32 v252, 16, v191
	v_and_b32_e32 v253, 0xffff0000, v191
	v_pk_add_f32 v[60:61], v[60:61], v[244:245]
	v_pk_add_f32 v[62:63], v[62:63], v[246:247]
	v_pk_add_f32 v[56:57], v[56:57], v[250:251]
	v_pk_add_f32 v[58:59], v[58:59], v[252:253]
	v_pk_mul_f32 v[254:255], v[60:61], v[60:61]
	v_pk_fma_f32 v[254:255], v[62:63], v[62:63], v[254:255]
	v_pk_fma_f32 v[254:255], v[56:57], v[56:57], v[254:255]
	v_pk_fma_f32 v[254:255], v[58:59], v[58:59], v[254:255]
	v_cvt_pk_bf16_f32 v60, v60, v61
	v_cvt_pk_bf16_f32 v61, v62, v63
	v_cvt_pk_bf16_f32 v62, v56, v57
	v_cvt_pk_bf16_f32 v63, v58, v59
	global_store_dwordx4 v232, v[60:63], s[20:21]
	s_waitcnt vmcnt(15)
	v_lshlrev_b32_e32 v244, 16, v192
	v_and_b32_e32 v245, 0xffff0000, v192
	v_lshlrev_b32_e32 v246, 16, v193
	v_and_b32_e32 v247, 0xffff0000, v193
	v_lshlrev_b32_e32 v250, 16, v194
	v_and_b32_e32 v251, 0xffff0000, v194
	v_lshlrev_b32_e32 v252, 16, v195
	v_and_b32_e32 v253, 0xffff0000, v195
	v_pk_add_f32 v[52:53], v[52:53], v[244:245]
	v_pk_add_f32 v[54:55], v[54:55], v[246:247]
	v_pk_add_f32 v[48:49], v[48:49], v[250:251]
	v_pk_add_f32 v[50:51], v[50:51], v[252:253]
	v_pk_fma_f32 v[254:255], v[52:53], v[52:53], v[254:255]
	v_pk_fma_f32 v[254:255], v[54:55], v[54:55], v[254:255]
	v_pk_fma_f32 v[254:255], v[48:49], v[48:49], v[254:255]
	v_pk_fma_f32 v[254:255], v[50:51], v[50:51], v[254:255]
	v_cvt_pk_bf16_f32 v52, v52, v53
	v_cvt_pk_bf16_f32 v53, v54, v55
	v_cvt_pk_bf16_f32 v54, v48, v49
	v_cvt_pk_bf16_f32 v55, v50, v51
	global_store_dwordx4 v232, v[52:55], s[20:21] offset:256
	v_add_f32_e32 v48, v254, v255
	s_waitcnt vmcnt(15)
	v_lshlrev_b32_e32 v244, 16, v196
	v_and_b32_e32 v245, 0xffff0000, v196
	v_lshlrev_b32_e32 v246, 16, v197
	v_and_b32_e32 v247, 0xffff0000, v197
	v_lshlrev_b32_e32 v250, 16, v198
	v_and_b32_e32 v251, 0xffff0000, v198
	v_lshlrev_b32_e32 v252, 16, v199
	v_and_b32_e32 v253, 0xffff0000, v199
	v_pk_add_f32 v[44:45], v[44:45], v[244:245]
	v_pk_add_f32 v[46:47], v[46:47], v[246:247]
	v_pk_add_f32 v[40:41], v[40:41], v[250:251]
	v_pk_add_f32 v[42:43], v[42:43], v[252:253]
	v_pk_mul_f32 v[254:255], v[44:45], v[44:45]
	v_pk_fma_f32 v[254:255], v[46:47], v[46:47], v[254:255]
	v_pk_fma_f32 v[254:255], v[40:41], v[40:41], v[254:255]
	v_pk_fma_f32 v[254:255], v[42:43], v[42:43], v[254:255]
	v_cvt_pk_bf16_f32 v44, v44, v45
	v_cvt_pk_bf16_f32 v45, v46, v47
	v_cvt_pk_bf16_f32 v46, v40, v41
	v_cvt_pk_bf16_f32 v47, v42, v43
	global_store_dwordx4 v233, v[44:47], s[20:21]
	s_waitcnt vmcnt(15)
	v_lshlrev_b32_e32 v244, 16, v200
	v_and_b32_e32 v245, 0xffff0000, v200
	v_lshlrev_b32_e32 v246, 16, v201
	v_and_b32_e32 v247, 0xffff0000, v201
	v_lshlrev_b32_e32 v250, 16, v202
	v_and_b32_e32 v251, 0xffff0000, v202
	v_lshlrev_b32_e32 v252, 16, v203
	v_and_b32_e32 v253, 0xffff0000, v203
	v_pk_add_f32 v[36:37], v[36:37], v[244:245]
	v_pk_add_f32 v[38:39], v[38:39], v[246:247]
	v_pk_add_f32 v[32:33], v[32:33], v[250:251]
	v_pk_add_f32 v[34:35], v[34:35], v[252:253]
	v_pk_fma_f32 v[254:255], v[36:37], v[36:37], v[254:255]
	v_pk_fma_f32 v[254:255], v[38:39], v[38:39], v[254:255]
	v_pk_fma_f32 v[254:255], v[32:33], v[32:33], v[254:255]
	v_pk_fma_f32 v[254:255], v[34:35], v[34:35], v[254:255]
	v_cvt_pk_bf16_f32 v36, v36, v37
	v_cvt_pk_bf16_f32 v37, v38, v39
	v_cvt_pk_bf16_f32 v38, v32, v33
	v_cvt_pk_bf16_f32 v39, v34, v35
	global_store_dwordx4 v233, v[36:39], s[20:21] offset:256
	v_add_f32_e32 v32, v254, v255
	s_waitcnt vmcnt(15)
	v_lshlrev_b32_e32 v244, 16, v204
	v_and_b32_e32 v245, 0xffff0000, v204
	v_lshlrev_b32_e32 v246, 16, v205
	v_and_b32_e32 v247, 0xffff0000, v205
	v_lshlrev_b32_e32 v250, 16, v206
	v_and_b32_e32 v251, 0xffff0000, v206
	v_lshlrev_b32_e32 v252, 16, v207
	v_and_b32_e32 v253, 0xffff0000, v207
	v_pk_add_f32 v[28:29], v[28:29], v[244:245]
	v_pk_add_f32 v[30:31], v[30:31], v[246:247]
	v_pk_add_f32 v[24:25], v[24:25], v[250:251]
	v_pk_add_f32 v[26:27], v[26:27], v[252:253]
	v_pk_mul_f32 v[254:255], v[28:29], v[28:29]
	v_pk_fma_f32 v[254:255], v[30:31], v[30:31], v[254:255]
	v_pk_fma_f32 v[254:255], v[24:25], v[24:25], v[254:255]
	v_pk_fma_f32 v[254:255], v[26:27], v[26:27], v[254:255]
	v_cvt_pk_bf16_f32 v28, v28, v29
	v_cvt_pk_bf16_f32 v29, v30, v31
	v_cvt_pk_bf16_f32 v30, v24, v25
	v_cvt_pk_bf16_f32 v31, v26, v27
	global_store_dwordx4 v234, v[28:31], s[20:21]
	s_waitcnt vmcnt(15)
	v_lshlrev_b32_e32 v244, 16, v208
	v_and_b32_e32 v245, 0xffff0000, v208
	v_lshlrev_b32_e32 v246, 16, v209
	v_and_b32_e32 v247, 0xffff0000, v209
	v_lshlrev_b32_e32 v250, 16, v210
	v_and_b32_e32 v251, 0xffff0000, v210
	v_lshlrev_b32_e32 v252, 16, v211
	v_and_b32_e32 v253, 0xffff0000, v211
	v_pk_add_f32 v[20:21], v[20:21], v[244:245]
	v_pk_add_f32 v[22:23], v[22:23], v[246:247]
	v_pk_add_f32 v[16:17], v[16:17], v[250:251]
	v_pk_add_f32 v[18:19], v[18:19], v[252:253]
	v_pk_fma_f32 v[254:255], v[20:21], v[20:21], v[254:255]
	v_pk_fma_f32 v[254:255], v[22:23], v[22:23], v[254:255]
	v_pk_fma_f32 v[254:255], v[16:17], v[16:17], v[254:255]
	v_pk_fma_f32 v[254:255], v[18:19], v[18:19], v[254:255]
	v_cvt_pk_bf16_f32 v20, v20, v21
	v_cvt_pk_bf16_f32 v21, v22, v23
	v_cvt_pk_bf16_f32 v22, v16, v17
	v_cvt_pk_bf16_f32 v23, v18, v19
	global_store_dwordx4 v234, v[20:23], s[20:21] offset:256
	v_add_f32_e32 v16, v254, v255
	s_waitcnt vmcnt(15)
	v_lshlrev_b32_e32 v244, 16, v212
	v_and_b32_e32 v245, 0xffff0000, v212
	v_lshlrev_b32_e32 v246, 16, v213
	v_and_b32_e32 v247, 0xffff0000, v213
	v_lshlrev_b32_e32 v250, 16, v214
	v_and_b32_e32 v251, 0xffff0000, v214
	v_lshlrev_b32_e32 v252, 16, v215
	v_and_b32_e32 v253, 0xffff0000, v215
	v_pk_add_f32 v[12:13], v[12:13], v[244:245]
	v_pk_add_f32 v[14:15], v[14:15], v[246:247]
	v_pk_add_f32 v[8:9], v[8:9], v[250:251]
	v_pk_add_f32 v[10:11], v[10:11], v[252:253]
	v_pk_mul_f32 v[254:255], v[12:13], v[12:13]
	v_pk_fma_f32 v[254:255], v[14:15], v[14:15], v[254:255]
	v_pk_fma_f32 v[254:255], v[8:9], v[8:9], v[254:255]
	v_pk_fma_f32 v[254:255], v[10:11], v[10:11], v[254:255]
	v_cvt_pk_bf16_f32 v12, v12, v13
	v_cvt_pk_bf16_f32 v13, v14, v15
	v_cvt_pk_bf16_f32 v14, v8, v9
	v_cvt_pk_bf16_f32 v15, v10, v11
	global_store_dwordx4 v235, v[12:15], s[20:21]
	s_waitcnt vmcnt(15)
	v_lshlrev_b32_e32 v244, 16, v224
	v_and_b32_e32 v245, 0xffff0000, v224
	v_lshlrev_b32_e32 v246, 16, v225
	v_and_b32_e32 v247, 0xffff0000, v225
	v_lshlrev_b32_e32 v250, 16, v226
	v_and_b32_e32 v251, 0xffff0000, v226
	v_lshlrev_b32_e32 v252, 16, v227
	v_and_b32_e32 v253, 0xffff0000, v227
	v_pk_add_f32 v[4:5], v[4:5], v[244:245]
	v_pk_add_f32 v[6:7], v[6:7], v[246:247]
	v_pk_add_f32 v[0:1], v[0:1], v[250:251]
	v_pk_add_f32 v[2:3], v[2:3], v[252:253]
	v_pk_fma_f32 v[254:255], v[4:5], v[4:5], v[254:255]
	v_pk_fma_f32 v[254:255], v[6:7], v[6:7], v[254:255]
	v_pk_fma_f32 v[254:255], v[0:1], v[0:1], v[254:255]
	v_pk_fma_f32 v[254:255], v[2:3], v[2:3], v[254:255]
	v_cvt_pk_bf16_f32 v4, v4, v5
	v_cvt_pk_bf16_f32 v5, v6, v7
	v_cvt_pk_bf16_f32 v6, v0, v1
	v_cvt_pk_bf16_f32 v7, v2, v3
	global_store_dwordx4 v235, v[4:7], s[20:21] offset:256
	v_add_f32_e32 v0, v254, v255
	v_xor_b32_e32 v244, 16, v154
	v_xor_b32_e32 v245, 32, v154
	v_lshlrev_b32_e32 v244, 2, v244
	v_lshlrev_b32_e32 v245, 2, v245
	ds_bpermute_b32 v156, v244, v112
	ds_bpermute_b32 v157, v244, v96
	ds_bpermute_b32 v158, v244, v80
	ds_bpermute_b32 v159, v244, v64
	ds_bpermute_b32 v160, v244, v48
	ds_bpermute_b32 v161, v244, v32
	ds_bpermute_b32 v162, v244, v16
	ds_bpermute_b32 v163, v244, v0
	s_waitcnt lgkmcnt(0)
	v_add_f32_e32 v112, v112, v156
	v_add_f32_e32 v96, v96, v157
	v_add_f32_e32 v80, v80, v158
	v_add_f32_e32 v64, v64, v159
	v_add_f32_e32 v48, v48, v160
	v_add_f32_e32 v32, v32, v161
	v_add_f32_e32 v16, v16, v162
	v_add_f32_e32 v0, v0, v163
	ds_bpermute_b32 v156, v245, v112
	ds_bpermute_b32 v157, v245, v96
	ds_bpermute_b32 v158, v245, v80
	ds_bpermute_b32 v159, v245, v64
	ds_bpermute_b32 v160, v245, v48
	ds_bpermute_b32 v161, v245, v32
	ds_bpermute_b32 v162, v245, v16
	ds_bpermute_b32 v163, v245, v0
	v_lshlrev_b32_e32 v145, 2, v146
	s_waitcnt lgkmcnt(0)
	v_add_f32_e32 v112, v112, v156
	v_add_f32_e32 v96, v96, v157
	v_add_f32_e32 v80, v80, v158
	v_add_f32_e32 v64, v64, v159
	v_add_f32_e32 v48, v48, v160
	v_add_f32_e32 v32, v32, v161
	v_add_f32_e32 v16, v16, v162
	v_add_f32_e32 v0, v0, v163
	s_and_saveexec_b64 s[46:47], s[0:1]
	s_cbranch_execz .Lepi_p4_noatom
	global_atomic_add_f32 v145, v112, s[22:23]
	global_atomic_add_f32 v145, v96, s[22:23] offset:64
	global_atomic_add_f32 v145, v80, s[22:23] offset:128
	global_atomic_add_f32 v145, v64, s[22:23] offset:192
	global_atomic_add_f32 v145, v48, s[22:23] offset:512
	global_atomic_add_f32 v145, v32, s[22:23] offset:576
	global_atomic_add_f32 v145, v16, s[22:23] offset:640
	global_atomic_add_f32 v145, v0, s[22:23] offset:704

.LBB0_568:
	s_lshl_b32 s0, s35, 1
	s_add_i32 s0, s0, s55
	s_mul_hi_i32 s1, s0, 0x7e07e07f
	s_lshr_b32 s13, s1, 31
	s_ashr_i32 s1, s1, 5
	s_add_i32 s1, s1, s13
	s_mul_i32 s77, s1, 0xffffffbf
	s_add_i32 s77, s77, s0
	s_mul_i32 s13, s77, 0x7e
	v_lshl_or_b32 v92, s1, 13, v204
	v_add_u32_e32 v174, s13, v92
	v_ashrrev_i32_e32 v175, 31, v174
	v_lshl_or_b32 v176, s16, 7, v206
	v_lshl_add_u64 v[92:93], v[174:175], 2, s[20:21]
	v_ashrrev_i32_e32 v177, 31, v176
	v_readlane_b32 s4, v249, 32
	global_load_dwordx4 v[198:201], v[92:93], off
	global_load_dwordx4 v[212:215], v[92:93], off offset:16
	v_lshlrev_b64 v[92:93], 2, v[176:177]
	v_readlane_b32 s5, v249, 33
	v_readlane_b32 s6, v249, 34
	v_readlane_b32 s7, v249, 35
	v_readlane_b32 s8, v249, 36
	v_readlane_b32 s9, v249, 37
	v_readlane_b32 s10, v249, 38
	v_readlane_b32 s11, v249, 39
	v_readlane_b32 s12, v249, 40
	v_readlane_b32 s13, v249, 41
	v_readlane_b32 s14, v249, 42
	v_readlane_b32 s15, v249, 43
	v_readlane_b32 s16, v249, 44
	v_readlane_b32 s17, v249, 45
	v_readlane_b32 s18, v249, 46
	v_readlane_b32 s19, v249, 47
	v_lshl_add_u64 v[134:135], s[36:37], 0, v[92:93]
	v_lshl_add_u64 v[138:139], s[38:39], 0, v[92:93]
	v_lshl_add_u64 v[194:195], s[18:19], 0, v[92:93]
	v_readlane_b32 s4, v249, 0
	v_readlane_b32 s5, v249, 1
	v_lshl_add_u64 v[146:147], s[40:41], 0, v[92:93]
	v_lshl_add_u64 v[150:151], s[42:43], 0, v[92:93]
	v_lshl_add_u64 v[196:197], s[4:5], 0, v[92:93]
	global_load_dwordx4 v[130:133], v[194:195], off
	s_nop 0
	global_load_dwordx4 v[134:137], v[134:135], off
	v_lshl_add_u64 v[154:155], s[44:45], 0, v[92:93]
	global_load_dwordx4 v[138:141], v[138:139], off
	v_lshl_add_u64 v[92:93], s[46:47], 0, v[92:93]
	global_load_dwordx4 v[142:145], v[196:197], off
	s_nop 0
	global_load_dwordx4 v[146:149], v[146:147], off
	s_nop 0
	global_load_dwordx4 v[150:153], v[150:151], off
	s_cmpk_lt_i32 s0, 0x208
	global_load_dwordx4 v[154:157], v[154:155], off
	v_readlane_b32 s12, v249, 8
	global_load_dwordx4 v[158:161], v[92:93], off
	v_readlane_b32 s13, v249, 9
	s_cselect_b64 s[0:1], -1, 0
	s_cmp_eq_u32 s77, 32
	s_cselect_b64 s[12:13], -1, 0
	s_and_b64 s[12:13], s[0:1], s[12:13]
	v_readlane_b32 s4, v249, 16
	s_and_b64 s[0:1], s[24:25], s[12:13]
	v_readlane_b32 s5, v249, 17
	v_readlane_b32 s6, v249, 2
	v_readlane_b32 s7, v249, 3
	v_readlane_b32 s8, v249, 4
	v_readlane_b32 s9, v249, 5
	v_readlane_b32 s10, v249, 6
	v_readlane_b32 s11, v249, 7
	v_readlane_b32 s14, v249, 10
	v_readlane_b32 s15, v249, 11
	v_readlane_b32 s16, v249, 12
	v_readlane_b32 s17, v249, 13
	v_readlane_b32 s18, v249, 14
	v_readlane_b32 s19, v249, 15
	s_and_b64 s[84:85], s[4:5], s[12:13]
	s_and_b64 vcc, exec, s[30:31]
	s_cbranch_vccz .Lp5ep_nobar
	s_barrier
.Lp5ep_nobar:
	s_waitcnt vmcnt(0)
	v_fmamk_f32 v92, v198, 0x3a800000, v210
	v_fmamk_f32 v93, v199, 0x3a800000, v210
	v_fmamk_f32 v175, v200, 0x3a800000, v210
	v_fmamk_f32 v178, v201, 0x3a800000, v210
	v_fmamk_f32 v180, v212, 0x3a800000, v210
	v_fmamk_f32 v192, v213, 0x3a800000, v210
	v_fmamk_f32 v198, v214, 0x3a800000, v210
	v_fmamk_f32 v199, v215, 0x3a800000, v210
	v_rsq_f32_e32 v190, v92
	v_rsq_f32_e32 v188, v93
	v_rsq_f32_e32 v186, v175
	v_rsq_f32_e32 v184, v178
	v_rsq_f32_e32 v182, v180
	v_rsq_f32_e32 v180, v192
	v_rsq_f32_e32 v178, v198
	v_rsq_f32_e32 v192, v199
	v_pk_mul_f32 v[212:213], v[126:127], v[190:191] op_sel_hi:[1,0]
	v_pk_mul_f32 v[126:127], v[106:107], v[192:193] op_sel_hi:[1,0]
	v_pk_mul_f32 v[118:119], v[118:119], v[188:189] op_sel_hi:[1,0]
	v_mov_b32_dpp v106, v212 row_shl:1 row_mask:0xf bank_mask:0xf bound_ctrl:1
	v_mov_b32_dpp v92, v126 row_shr:1 row_mask:0xf bank_mask:0xf bound_ctrl:1
	v_mov_b32_dpp v93, v127 row_shr:1 row_mask:0xf bank_mask:0xf bound_ctrl:1
	v_cndmask_b32_e64 v93, v93, 0, s[84:85]
	v_cndmask_b32_e64 v92, v92, 0, s[84:85]
	v_pk_fma_f32 v[92:93], v[130:131], v[92:93], v[142:143]
	v_mov_b32_dpp v107, v213 row_shl:1 row_mask:0xf bank_mask:0xf bound_ctrl:1
	v_pk_fma_f32 v[92:93], v[134:135], v[212:213], v[92:93]
	v_cndmask_b32_e64 v199, v107, 0, s[0:1]
	v_pk_fma_f32 v[92:93], v[138:139], v[118:119], v[92:93]
	v_cndmask_b32_e64 v198, v106, 0, s[0:1]
	v_pk_mul_f32 v[106:107], v[92:93], s[48:49] op_sel_hi:[1,0]
	s_mov_b32 s12, 0x3b5f5da2
	v_med3_f32 v220, v106, s97, v211
	v_med3_f32 v221, v107, s97, v211
	v_pk_mul_f32 v[224:225], v[220:221], v[220:221]
	v_mov_b64_e32 v[106:107], s[12:13]
	v_pk_mul_f32 v[216:217], v[114:115], v[188:189] op_sel_hi:[1,0]
	v_pk_fma_f32 v[114:115], v[224:225], s[52:53], v[106:107] op_sel_hi:[1,0,0]
	s_mov_b32 s12, 0x37c588df
	v_pk_fma_f32 v[226:227], v[224:225], v[114:115], s[54:55] op_sel_hi:[1,1,0]
	v_mov_b64_e32 v[114:115], s[12:13]
	v_pk_fma_f32 v[228:229], v[224:225], s[60:61], v[114:115] op_sel_hi:[1,0,0] neg_lo:[1,0,0] neg_hi:[1,0,0]
	v_pk_mul_f32 v[214:215], v[122:123], v[190:191] op_sel_hi:[1,0]
	v_pk_fma_f32 v[228:229], v[224:225], v[228:229], s[62:63] op_sel_hi:[1,1,0]
	v_pk_mul_f32 v[122:123], v[98:99], v[192:193] op_sel_hi:[1,0]
	v_pk_fma_f32 v[228:229], v[224:225], v[228:229], s[66:67] op_sel_hi:[1,1,0]
	v_pk_fma_f32 v[226:227], v[224:225], v[226:227], s[56:57] op_sel_hi:[1,1,0]
	v_pk_fma_f32 v[228:229], v[224:225], v[228:229], s[72:73] op_sel_hi:[1,1,0]
	v_mov_b32_dpp v98, v122 row_shr:1 row_mask:0xf bank_mask:0xf bound_ctrl:1
	v_pk_fma_f32 v[228:229], v[224:225], v[228:229], s[74:75] op_sel_hi:[1,1,0]
	v_mov_b32_dpp v99, v123 row_shr:1 row_mask:0xf bank_mask:0xf bound_ctrl:1
	v_pk_fma_f32 v[228:229], v[224:225], v[228:229], 1.0 op_sel_hi:[1,1,0]
	v_cndmask_b32_e64 v99, v99, 0, s[84:85]
	v_rcp_f32_e32 v228, v228
	v_rcp_f32_e32 v229, v229
	v_cndmask_b32_e64 v98, v98, 0, s[84:85]
	v_pk_fma_f32 v[224:225], v[224:225], v[226:227], s[58:59] op_sel_hi:[1,1,0]
	v_pk_fma_f32 v[98:99], v[146:147], v[98:99], v[158:159]
	v_pk_mul_f32 v[220:221], v[220:221], v[224:225]
	v_pk_fma_f32 v[98:99], v[150:151], v[214:215], v[98:99]
	v_pk_mul_f32 v[220:221], v[220:221], v[228:229]
	v_pk_mul_f32 v[92:93], v[92:93], 0.5 op_sel_hi:[1,0]
	v_pk_fma_f32 v[98:99], v[154:155], v[216:217], v[98:99]
	v_pk_fma_f32 v[92:93], v[92:93], v[220:221], v[92:93]
	v_pk_mul_f32 v[110:111], v[110:111], v[186:187] op_sel_hi:[1,0]
	v_pk_mul_f32 v[92:93], v[98:99], v[92:93]
	v_pk_fma_f32 v[98:99], v[130:131], v[212:213], v[142:143]
	v_mov_b32_dpp v175, v214 row_shl:1 row_mask:0xf bank_mask:0xf bound_ctrl:1
	v_pk_fma_f32 v[98:99], v[134:135], v[118:119], v[98:99]
	v_mov_b32_dpp v200, v215 row_shl:1 row_mask:0xf bank_mask:0xf bound_ctrl:1
	v_pk_fma_f32 v[98:99], v[138:139], v[110:111], v[98:99]
	v_pk_fma_f32 v[212:213], v[146:147], v[214:215], v[158:159]
	v_pk_mul_f32 v[214:215], v[98:99], s[48:49] op_sel_hi:[1,0]
	v_pk_mul_f32 v[102:103], v[102:103], v[186:187] op_sel_hi:[1,0]
	v_med3_f32 v214, v214, s97, v211
	v_med3_f32 v215, v215, s97, v211
	v_pk_mul_f32 v[220:221], v[214:215], v[214:215]
	v_pk_fma_f32 v[212:213], v[150:151], v[216:217], v[212:213]
	v_pk_fma_f32 v[226:227], v[220:221], s[60:61], v[114:115] op_sel_hi:[1,0,0] neg_lo:[1,0,0] neg_hi:[1,0,0]
	v_pk_fma_f32 v[224:225], v[220:221], s[52:53], v[106:107] op_sel_hi:[1,0,0]
	v_pk_fma_f32 v[226:227], v[220:221], v[226:227], s[62:63] op_sel_hi:[1,1,0]
	v_pk_fma_f32 v[224:225], v[220:221], v[224:225], s[54:55] op_sel_hi:[1,1,0]
	v_pk_fma_f32 v[226:227], v[220:221], v[226:227], s[66:67] op_sel_hi:[1,1,0]
	v_pk_fma_f32 v[224:225], v[220:221], v[224:225], s[56:57] op_sel_hi:[1,1,0]
	v_pk_fma_f32 v[226:227], v[220:221], v[226:227], s[72:73] op_sel_hi:[1,1,0]
	v_pk_mul_f32 v[98:99], v[98:99], 0.5 op_sel_hi:[1,0]
	v_pk_fma_f32 v[226:227], v[220:221], v[226:227], s[74:75] op_sel_hi:[1,1,0]
	v_pk_fma_f32 v[212:213], v[154:155], v[102:103], v[212:213]
	v_pk_fma_f32 v[226:227], v[220:221], v[226:227], 1.0 op_sel_hi:[1,1,0]
	v_pk_fma_f32 v[220:221], v[220:221], v[224:225], s[58:59] op_sel_hi:[1,1,0]
	v_rcp_f32_e32 v226, v226
	v_rcp_f32_e32 v227, v227
	v_pk_mul_f32 v[214:215], v[214:215], v[220:221]
	v_pk_mul_f32 v[94:95], v[94:95], v[184:185] op_sel_hi:[1,0]
	v_pk_mul_f32 v[84:85], v[84:85], v[182:183] op_sel_hi:[1,0]
	v_pk_mul_f32 v[214:215], v[214:215], v[226:227]
	v_pk_mul_f32 v[76:77], v[76:77], v[180:181] op_sel_hi:[1,0]
	v_pk_fma_f32 v[98:99], v[98:99], v[214:215], v[98:99]
	v_cndmask_b32_e64 v201, v200, 0, s[0:1]
	v_pk_mul_f32 v[98:99], v[212:213], v[98:99]
	v_pk_mul_f32 v[212:213], v[88:89], v[184:185] op_sel_hi:[1,0]
	v_pk_fma_f32 v[88:89], v[130:131], v[118:119], v[142:143]
	v_pk_fma_f32 v[118:119], v[146:147], v[216:217], v[158:159]
	v_pk_fma_f32 v[88:89], v[134:135], v[110:111], v[88:89]
	v_pk_fma_f32 v[118:119], v[150:151], v[102:103], v[118:119]
	v_pk_fma_f32 v[88:89], v[138:139], v[94:95], v[88:89]
	v_pk_fma_f32 v[118:119], v[154:155], v[212:213], v[118:119]
	v_pk_mul_f32 v[214:215], v[88:89], s[48:49] op_sel_hi:[1,0]
	v_pk_mul_f32 v[88:89], v[88:89], 0.5 op_sel_hi:[1,0]
	v_med3_f32 v214, v214, s97, v211
	v_med3_f32 v215, v215, s97, v211
	v_pk_mul_f32 v[216:217], v[214:215], v[214:215]
	v_pk_fma_f32 v[102:103], v[146:147], v[102:103], v[158:159]
	v_pk_fma_f32 v[224:225], v[216:217], s[60:61], v[114:115] op_sel_hi:[1,0,0] neg_lo:[1,0,0] neg_hi:[1,0,0]
	v_pk_fma_f32 v[220:221], v[216:217], s[52:53], v[106:107] op_sel_hi:[1,0,0]
	v_pk_fma_f32 v[224:225], v[216:217], v[224:225], s[62:63] op_sel_hi:[1,1,0]
	v_pk_fma_f32 v[220:221], v[216:217], v[220:221], s[54:55] op_sel_hi:[1,1,0]
	v_pk_fma_f32 v[224:225], v[216:217], v[224:225], s[66:67] op_sel_hi:[1,1,0]
	v_pk_fma_f32 v[220:221], v[216:217], v[220:221], s[56:57] op_sel_hi:[1,1,0]
	v_pk_fma_f32 v[224:225], v[216:217], v[224:225], s[72:73] op_sel_hi:[1,1,0]
	v_pk_fma_f32 v[102:103], v[150:151], v[212:213], v[102:103]
	v_pk_fma_f32 v[224:225], v[216:217], v[224:225], s[74:75] op_sel_hi:[1,1,0]
	v_cndmask_b32_e64 v200, v175, 0, s[0:1]
	v_pk_fma_f32 v[224:225], v[216:217], v[224:225], 1.0 op_sel_hi:[1,1,0]
	v_pk_fma_f32 v[216:217], v[216:217], v[220:221], s[58:59] op_sel_hi:[1,1,0]
	v_rcp_f32_e32 v224, v224
	v_rcp_f32_e32 v225, v225
	v_pk_mul_f32 v[214:215], v[214:215], v[216:217]
	v_cvt_pk_bf16_f32 v92, v92, v93
	v_cvt_pk_bf16_f32 v98, v98, v99
	s_nop 0
	v_pk_mul_f32 v[214:215], v[214:215], v[224:225]
	s_nop 0
	v_pk_fma_f32 v[88:89], v[88:89], v[214:215], v[88:89]
	s_nop 0
	v_pk_mul_f32 v[88:89], v[118:119], v[88:89]
	v_pk_mul_f32 v[118:119], v[80:81], v[182:183] op_sel_hi:[1,0]
	v_pk_fma_f32 v[80:81], v[130:131], v[110:111], v[142:143]
	v_pk_fma_f32 v[102:103], v[154:155], v[118:119], v[102:103]
	v_pk_fma_f32 v[80:81], v[134:135], v[94:95], v[80:81]
	v_cvt_pk_bf16_f32 v88, v88, v89
	s_nop 0
	v_pk_fma_f32 v[80:81], v[138:139], v[84:85], v[80:81]
	s_nop 0
	v_pk_mul_f32 v[110:111], v[80:81], s[48:49] op_sel_hi:[1,0]
	v_pk_mul_f32 v[80:81], v[80:81], 0.5 op_sel_hi:[1,0]
	v_med3_f32 v110, v110, s97, v211
	v_med3_f32 v111, v111, s97, v211
	v_pk_mul_f32 v[214:215], v[110:111], v[110:111]
	s_nop 0
	v_pk_fma_f32 v[220:221], v[214:215], s[60:61], v[114:115] op_sel_hi:[1,0,0] neg_lo:[1,0,0] neg_hi:[1,0,0]
	v_pk_fma_f32 v[216:217], v[214:215], s[52:53], v[106:107] op_sel_hi:[1,0,0]
	v_pk_fma_f32 v[220:221], v[214:215], v[220:221], s[62:63] op_sel_hi:[1,1,0]
	v_pk_fma_f32 v[216:217], v[214:215], v[216:217], s[54:55] op_sel_hi:[1,1,0]
	v_pk_fma_f32 v[220:221], v[214:215], v[220:221], s[66:67] op_sel_hi:[1,1,0]
	v_pk_fma_f32 v[216:217], v[214:215], v[216:217], s[56:57] op_sel_hi:[1,1,0]
	v_pk_fma_f32 v[220:221], v[214:215], v[220:221], s[72:73] op_sel_hi:[1,1,0]
	s_nop 0
	v_pk_fma_f32 v[220:221], v[214:215], v[220:221], s[74:75] op_sel_hi:[1,1,0]
	s_nop 0
	v_pk_fma_f32 v[220:221], v[214:215], v[220:221], 1.0 op_sel_hi:[1,1,0]
	v_pk_fma_f32 v[214:215], v[214:215], v[216:217], s[58:59] op_sel_hi:[1,1,0]
	v_rcp_f32_e32 v220, v220
	v_rcp_f32_e32 v221, v221
	v_pk_mul_f32 v[110:111], v[110:111], v[214:215]
	s_nop 0
	v_pk_mul_f32 v[110:111], v[110:111], v[220:221]
	s_nop 0
	v_pk_fma_f32 v[80:81], v[80:81], v[110:111], v[80:81]
	s_nop 0
	v_pk_mul_f32 v[80:81], v[102:103], v[80:81]
	v_pk_mul_f32 v[102:103], v[72:73], v[180:181] op_sel_hi:[1,0]
	v_pk_fma_f32 v[72:73], v[130:131], v[94:95], v[142:143]
	v_pk_fma_f32 v[94:95], v[146:147], v[212:213], v[158:159]
	v_pk_fma_f32 v[72:73], v[134:135], v[84:85], v[72:73]
	v_pk_fma_f32 v[94:95], v[150:151], v[118:119], v[94:95]
	v_pk_fma_f32 v[72:73], v[138:139], v[76:77], v[72:73]
	v_pk_fma_f32 v[94:95], v[154:155], v[102:103], v[94:95]
	v_pk_mul_f32 v[110:111], v[72:73], s[48:49] op_sel_hi:[1,0]
	v_pk_mul_f32 v[72:73], v[72:73], 0.5 op_sel_hi:[1,0]
	v_med3_f32 v110, v110, s97, v211
	v_med3_f32 v111, v111, s97, v211
	v_pk_mul_f32 v[212:213], v[110:111], v[110:111]
	v_cvt_pk_bf16_f32 v80, v80, v81
	s_nop 0
	v_pk_fma_f32 v[216:217], v[212:213], s[60:61], v[114:115] op_sel_hi:[1,0,0] neg_lo:[1,0,0] neg_hi:[1,0,0]
	v_pk_fma_f32 v[214:215], v[212:213], s[52:53], v[106:107] op_sel_hi:[1,0,0]
	v_pk_fma_f32 v[216:217], v[212:213], v[216:217], s[62:63] op_sel_hi:[1,1,0]
	v_pk_fma_f32 v[214:215], v[212:213], v[214:215], s[54:55] op_sel_hi:[1,1,0]
	v_pk_fma_f32 v[216:217], v[212:213], v[216:217], s[66:67] op_sel_hi:[1,1,0]
	v_pk_fma_f32 v[214:215], v[212:213], v[214:215], s[56:57] op_sel_hi:[1,1,0]
	v_pk_fma_f32 v[216:217], v[212:213], v[216:217], s[72:73] op_sel_hi:[1,1,0]
	s_nop 0
	v_pk_fma_f32 v[216:217], v[212:213], v[216:217], s[74:75] op_sel_hi:[1,1,0]
	s_nop 0
	v_pk_fma_f32 v[216:217], v[212:213], v[216:217], 1.0 op_sel_hi:[1,1,0]
	v_pk_fma_f32 v[212:213], v[212:213], v[214:215], s[58:59] op_sel_hi:[1,1,0]
	v_rcp_f32_e32 v216, v216
	v_rcp_f32_e32 v217, v217
	v_pk_mul_f32 v[110:111], v[110:111], v[212:213]
	s_nop 0
	v_pk_mul_f32 v[110:111], v[110:111], v[216:217]
	s_nop 0
	v_pk_fma_f32 v[72:73], v[72:73], v[110:111], v[72:73]
	v_pk_mul_f32 v[110:111], v[64:65], v[178:179] op_sel_hi:[1,0]
	v_pk_fma_f32 v[64:65], v[130:131], v[84:85], v[142:143]
	v_pk_mul_f32 v[72:73], v[94:95], v[72:73]
	v_pk_mul_f32 v[94:95], v[68:69], v[178:179] op_sel_hi:[1,0]
	v_pk_fma_f32 v[64:65], v[134:135], v[76:77], v[64:65]
	v_pk_fma_f32 v[68:69], v[146:147], v[118:119], v[158:159]
	v_pk_fma_f32 v[64:65], v[138:139], v[94:95], v[64:65]
	v_pk_fma_f32 v[68:69], v[150:151], v[102:103], v[68:69]
	v_pk_mul_f32 v[84:85], v[64:65], s[48:49] op_sel_hi:[1,0]
	v_pk_mul_f32 v[64:65], v[64:65], 0.5 op_sel_hi:[1,0]
	v_med3_f32 v84, v84, s97, v211
	v_med3_f32 v85, v85, s97, v211
	v_pk_mul_f32 v[118:119], v[84:85], v[84:85]
	v_pk_fma_f32 v[68:69], v[154:155], v[110:111], v[68:69]
	v_pk_fma_f32 v[214:215], v[118:119], s[60:61], v[114:115] op_sel_hi:[1,0,0] neg_lo:[1,0,0] neg_hi:[1,0,0]
	v_pk_fma_f32 v[212:213], v[118:119], s[52:53], v[106:107] op_sel_hi:[1,0,0]
	v_pk_fma_f32 v[214:215], v[118:119], v[214:215], s[62:63] op_sel_hi:[1,1,0]
	v_pk_fma_f32 v[212:213], v[118:119], v[212:213], s[54:55] op_sel_hi:[1,1,0]
	v_pk_fma_f32 v[214:215], v[118:119], v[214:215], s[66:67] op_sel_hi:[1,1,0]
	v_pk_fma_f32 v[212:213], v[118:119], v[212:213], s[56:57] op_sel_hi:[1,1,0]
	v_pk_fma_f32 v[214:215], v[118:119], v[214:215], s[72:73] op_sel_hi:[1,1,0]
	v_cvt_pk_bf16_f32 v72, v72, v73
	s_nop 0
	v_pk_fma_f32 v[214:215], v[118:119], v[214:215], s[74:75] op_sel_hi:[1,1,0]
	s_nop 0
	v_pk_fma_f32 v[214:215], v[118:119], v[214:215], 1.0 op_sel_hi:[1,1,0]
	v_pk_fma_f32 v[118:119], v[118:119], v[212:213], s[58:59] op_sel_hi:[1,1,0]
	v_rcp_f32_e32 v214, v214
	v_rcp_f32_e32 v215, v215
	v_pk_mul_f32 v[84:85], v[84:85], v[118:119]
	s_nop 0
	v_pk_mul_f32 v[84:85], v[84:85], v[214:215]
	s_nop 0
	v_pk_fma_f32 v[64:65], v[64:65], v[84:85], v[64:65]
	s_nop 0
	v_pk_mul_f32 v[64:65], v[68:69], v[64:65]
	v_pk_fma_f32 v[68:69], v[130:131], v[76:77], v[142:143]
	v_pk_fma_f32 v[76:77], v[146:147], v[102:103], v[158:159]
	v_pk_fma_f32 v[68:69], v[134:135], v[94:95], v[68:69]
	v_pk_fma_f32 v[76:77], v[150:151], v[110:111], v[76:77]
	v_pk_fma_f32 v[68:69], v[138:139], v[126:127], v[68:69]
	v_pk_fma_f32 v[76:77], v[154:155], v[122:123], v[76:77]
	v_pk_mul_f32 v[84:85], v[68:69], s[48:49] op_sel_hi:[1,0]
	v_pk_mul_f32 v[68:69], v[68:69], 0.5 op_sel_hi:[1,0]
	v_med3_f32 v84, v84, s97, v211
	v_med3_f32 v85, v85, s97, v211
	v_pk_mul_f32 v[102:103], v[84:85], v[84:85]
	v_cvt_pk_bf16_f32 v64, v64, v65
	s_nop 0
	v_pk_fma_f32 v[212:213], v[102:103], s[60:61], v[114:115] op_sel_hi:[1,0,0] neg_lo:[1,0,0] neg_hi:[1,0,0]
	v_pk_fma_f32 v[118:119], v[102:103], s[52:53], v[106:107] op_sel_hi:[1,0,0]
	v_pk_fma_f32 v[212:213], v[102:103], v[212:213], s[62:63] op_sel_hi:[1,1,0]
	v_pk_fma_f32 v[118:119], v[102:103], v[118:119], s[54:55] op_sel_hi:[1,1,0]
	v_pk_fma_f32 v[212:213], v[102:103], v[212:213], s[66:67] op_sel_hi:[1,1,0]
	v_pk_fma_f32 v[118:119], v[102:103], v[118:119], s[56:57] op_sel_hi:[1,1,0]
	v_pk_fma_f32 v[212:213], v[102:103], v[212:213], s[72:73] op_sel_hi:[1,1,0]
	s_nop 0
	v_pk_fma_f32 v[212:213], v[102:103], v[212:213], s[74:75] op_sel_hi:[1,1,0]
	s_nop 0
	v_pk_fma_f32 v[212:213], v[102:103], v[212:213], 1.0 op_sel_hi:[1,1,0]
	v_pk_fma_f32 v[102:103], v[102:103], v[118:119], s[58:59] op_sel_hi:[1,1,0]
	v_rcp_f32_e32 v212, v212
	v_rcp_f32_e32 v213, v213
	v_pk_mul_f32 v[84:85], v[84:85], v[102:103]
	s_nop 0
	v_pk_mul_f32 v[84:85], v[84:85], v[212:213]
	s_nop 0
	v_pk_fma_f32 v[68:69], v[68:69], v[84:85], v[68:69]
	v_pk_fma_f32 v[84:85], v[146:147], v[110:111], v[158:159]
	v_pk_mul_f32 v[68:69], v[76:77], v[68:69]
	v_pk_fma_f32 v[76:77], v[130:131], v[94:95], v[142:143]
	v_pk_fma_f32 v[84:85], v[150:151], v[122:123], v[84:85]
	v_pk_fma_f32 v[76:77], v[134:135], v[126:127], v[76:77]
	v_pk_fma_f32 v[84:85], v[154:155], v[200:201], v[84:85]
	v_pk_fma_f32 v[76:77], v[138:139], v[198:199], v[76:77]
	v_cvt_pk_bf16_f32 v68, v68, v69
	s_nop 0
	v_pk_mul_f32 v[94:95], v[76:77], s[48:49] op_sel_hi:[1,0]
	v_pk_mul_f32 v[76:77], v[76:77], 0.5 op_sel_hi:[1,0]
	v_med3_f32 v94, v94, s97, v211
	v_med3_f32 v95, v95, s97, v211
	v_pk_mul_f32 v[102:103], v[94:95], v[94:95]
	s_nop 0
	v_pk_fma_f32 v[118:119], v[102:103], s[60:61], v[114:115] op_sel_hi:[1,0,0] neg_lo:[1,0,0] neg_hi:[1,0,0]
	v_pk_fma_f32 v[110:111], v[102:103], s[52:53], v[106:107] op_sel_hi:[1,0,0]
	v_pk_fma_f32 v[118:119], v[102:103], v[118:119], s[62:63] op_sel_hi:[1,1,0]
	v_pk_fma_f32 v[110:111], v[102:103], v[110:111], s[54:55] op_sel_hi:[1,1,0]
	v_pk_fma_f32 v[118:119], v[102:103], v[118:119], s[66:67] op_sel_hi:[1,1,0]
	v_pk_fma_f32 v[110:111], v[102:103], v[110:111], s[56:57] op_sel_hi:[1,1,0]
	v_pk_fma_f32 v[118:119], v[102:103], v[118:119], s[72:73] op_sel_hi:[1,1,0]
	s_nop 0
	v_pk_fma_f32 v[118:119], v[102:103], v[118:119], s[74:75] op_sel_hi:[1,1,0]
	s_nop 0
	v_pk_fma_f32 v[118:119], v[102:103], v[118:119], 1.0 op_sel_hi:[1,1,0]
	v_pk_fma_f32 v[102:103], v[102:103], v[110:111], s[58:59] op_sel_hi:[1,1,0]
	v_rcp_f32_e32 v118, v118
	v_rcp_f32_e32 v119, v119
	v_pk_mul_f32 v[94:95], v[94:95], v[102:103]
	s_nop 0
	v_pk_mul_f32 v[94:95], v[94:95], v[118:119]
	s_nop 0
	v_pk_fma_f32 v[76:77], v[76:77], v[94:95], v[76:77]
	v_or_b32_e32 v94, 4, v176
	v_ashrrev_i32_e32 v95, 31, v94
	v_lshlrev_b64 v[94:95], 2, v[94:95]
	v_pk_mul_f32 v[76:77], v[84:85], v[76:77]
	v_lshl_add_u64 v[110:111], s[36:37], 0, v[94:95]
	v_lshl_add_u64 v[118:119], s[38:39], 0, v[94:95]
	v_lshl_add_u64 v[122:123], s[40:41], 0, v[94:95]
	v_lshl_add_u64 v[126:127], s[42:43], 0, v[94:95]
	v_cvt_pk_bf16_f32 v76, v76, v77
	global_load_dwordx2 v[84:85], v[194:195], off offset:16
	global_load_dwordx2 v[102:103], v[196:197], off offset:16
	s_nop 0
	global_load_dwordx2 v[110:111], v[110:111], off
	s_nop 0
	global_load_dwordx2 v[118:119], v[118:119], off
	s_nop 0
	global_load_dwordx2 v[122:123], v[122:123], off
	s_nop 0
	global_load_dwordx2 v[126:127], v[126:127], off
	v_lshl_add_u64 v[130:131], s[44:45], 0, v[94:95]
	v_lshl_add_u64 v[94:95], s[46:47], 0, v[94:95]
	global_load_dwordx2 v[130:131], v[130:131], off
	s_nop 0
	global_load_dwordx2 v[134:135], v[94:95], off
	v_pk_mul_f32 v[94:95], v[108:109], v[192:193] op_sel_hi:[1,0]
	v_pk_mul_f32 v[128:129], v[128:129], v[190:191] op_sel_hi:[1,0]
	v_pk_mul_f32 v[120:121], v[120:121], v[188:189] op_sel_hi:[1,0]
	v_mov_b32_dpp v65, v94 row_shr:1 row_mask:0xf bank_mask:0xf bound_ctrl:1
	v_mov_b32_dpp v69, v95 row_shr:1 row_mask:0xf bank_mask:0xf bound_ctrl:1
	v_cndmask_b32_e64 v143, v69, 0, s[84:85]
	v_cndmask_b32_e64 v142, v65, 0, s[84:85]
	v_pk_fma_f32 v[142:143], v[132:133], v[142:143], v[144:145]
	v_pk_mul_f32 v[100:101], v[100:101], v[192:193] op_sel_hi:[1,0]
	v_pk_fma_f32 v[142:143], v[128:129], v[136:137], v[142:143]
	v_pk_mul_f32 v[138:139], v[124:125], v[190:191] op_sel_hi:[1,0]
	v_pk_fma_f32 v[142:143], v[120:121], v[140:141], v[142:143]
	v_mov_b32_dpp v73, v100 row_shr:1 row_mask:0xf bank_mask:0xf bound_ctrl:1
	v_pk_mul_f32 v[150:151], v[142:143], s[48:49] op_sel_hi:[1,0]
	v_mov_b32_dpp v77, v101 row_shr:1 row_mask:0xf bank_mask:0xf bound_ctrl:1
	v_med3_f32 v150, v150, s97, v211
	v_med3_f32 v151, v151, s97, v211
	v_pk_mul_f32 v[154:155], v[150:151], v[150:151]
	v_cndmask_b32_e64 v147, v77, 0, s[84:85]
	v_pk_fma_f32 v[198:199], v[154:155], s[60:61], v[114:115] op_sel_hi:[1,0,0] neg_lo:[1,0,0] neg_hi:[1,0,0]
	v_pk_fma_f32 v[158:159], v[154:155], s[52:53], v[106:107] op_sel_hi:[1,0,0]
	v_pk_fma_f32 v[198:199], v[154:155], v[198:199], s[62:63] op_sel_hi:[1,1,0]
	v_pk_fma_f32 v[158:159], v[154:155], v[158:159], s[54:55] op_sel_hi:[1,1,0]
	v_pk_fma_f32 v[198:199], v[154:155], v[198:199], s[66:67] op_sel_hi:[1,1,0]
	v_pk_fma_f32 v[158:159], v[154:155], v[158:159], s[56:57] op_sel_hi:[1,1,0]
	v_pk_fma_f32 v[198:199], v[154:155], v[198:199], s[72:73] op_sel_hi:[1,1,0]
	v_cndmask_b32_e64 v146, v73, 0, s[84:85]
	v_pk_fma_f32 v[198:199], v[154:155], v[198:199], s[74:75] op_sel_hi:[1,1,0]
	v_pk_fma_f32 v[146:147], v[148:149], v[146:147], v[160:161]
	v_pk_fma_f32 v[198:199], v[154:155], v[198:199], 1.0 op_sel_hi:[1,1,0]
	v_pk_fma_f32 v[154:155], v[154:155], v[158:159], s[58:59] op_sel_hi:[1,1,0]
	v_rcp_f32_e32 v198, v198
	v_rcp_f32_e32 v199, v199
	v_pk_mul_f32 v[150:151], v[150:151], v[154:155]
	v_mov_b32_dpp v81, v128 row_shl:1 row_mask:0xf bank_mask:0xf bound_ctrl:1
	v_mov_b32_dpp v89, v129 row_shl:1 row_mask:0xf bank_mask:0xf bound_ctrl:1
	v_pk_mul_f32 v[116:117], v[116:117], v[188:189] op_sel_hi:[1,0]
	v_pk_fma_f32 v[146:147], v[138:139], v[152:153], v[146:147]
	v_pk_mul_f32 v[150:151], v[150:151], v[198:199]
	v_pk_mul_f32 v[142:143], v[142:143], 0.5 op_sel_hi:[1,0]
	v_pk_fma_f32 v[128:129], v[128:129], v[132:133], v[144:145]
	v_pk_fma_f32 v[146:147], v[116:117], v[156:157], v[146:147]
	v_pk_fma_f32 v[142:143], v[142:143], v[150:151], v[142:143]
	v_pk_mul_f32 v[112:113], v[112:113], v[186:187] op_sel_hi:[1,0]
	v_pk_fma_f32 v[128:129], v[120:121], v[136:137], v[128:129]
	v_mov_b32_dpp v93, v138 row_shl:1 row_mask:0xf bank_mask:0xf bound_ctrl:1
	v_pk_mul_f32 v[142:143], v[146:147], v[142:143]
	v_pk_fma_f32 v[128:129], v[112:113], v[140:141], v[128:129]
	v_cndmask_b32_e64 v124, v93, 0, s[0:1]
	v_cvt_pk_bf16_f32 v93, v142, v143
	v_pk_mul_f32 v[142:143], v[128:129], s[48:49] op_sel_hi:[1,0]
	v_mov_b32_dpp v99, v139 row_shl:1 row_mask:0xf bank_mask:0xf bound_ctrl:1
	v_med3_f32 v142, v142, s97, v211
	v_med3_f32 v143, v143, s97, v211
	v_pk_mul_f32 v[146:147], v[142:143], v[142:143]
	v_pk_fma_f32 v[138:139], v[138:139], v[148:149], v[160:161]
	v_pk_fma_f32 v[154:155], v[146:147], s[60:61], v[114:115] op_sel_hi:[1,0,0] neg_lo:[1,0,0] neg_hi:[1,0,0]
	v_pk_fma_f32 v[150:151], v[146:147], s[52:53], v[106:107] op_sel_hi:[1,0,0]
	v_pk_fma_f32 v[154:155], v[146:147], v[154:155], s[62:63] op_sel_hi:[1,1,0]
	v_pk_fma_f32 v[150:151], v[146:147], v[150:151], s[54:55] op_sel_hi:[1,1,0]
	v_pk_fma_f32 v[154:155], v[146:147], v[154:155], s[66:67] op_sel_hi:[1,1,0]
	v_pk_fma_f32 v[150:151], v[146:147], v[150:151], s[56:57] op_sel_hi:[1,1,0]
	v_pk_fma_f32 v[154:155], v[146:147], v[154:155], s[72:73] op_sel_hi:[1,1,0]
	v_pk_mul_f32 v[104:105], v[104:105], v[186:187] op_sel_hi:[1,0]
	v_pk_fma_f32 v[154:155], v[146:147], v[154:155], s[74:75] op_sel_hi:[1,1,0]
	v_pk_fma_f32 v[138:139], v[116:117], v[152:153], v[138:139]
	v_pk_fma_f32 v[154:155], v[146:147], v[154:155], 1.0 op_sel_hi:[1,1,0]
	v_pk_fma_f32 v[146:147], v[146:147], v[150:151], s[58:59] op_sel_hi:[1,1,0]
	v_rcp_f32_e32 v154, v154
	v_rcp_f32_e32 v155, v155
	v_pk_mul_f32 v[142:143], v[142:143], v[146:147]
	v_pk_mul_f32 v[128:129], v[128:129], 0.5 op_sel_hi:[1,0]
	v_pk_fma_f32 v[120:121], v[120:121], v[132:133], v[144:145]
	v_pk_mul_f32 v[142:143], v[142:143], v[154:155]
	v_pk_fma_f32 v[138:139], v[104:105], v[156:157], v[138:139]
	v_pk_fma_f32 v[128:129], v[128:129], v[142:143], v[128:129]
	v_pk_mul_f32 v[96:97], v[96:97], v[184:185] op_sel_hi:[1,0]
	v_pk_fma_f32 v[120:121], v[112:113], v[136:137], v[120:121]
	v_pk_mul_f32 v[128:129], v[138:139], v[128:129]
	v_pk_fma_f32 v[120:121], v[96:97], v[140:141], v[120:121]
	v_cndmask_b32_e64 v125, v99, 0, s[0:1]
	v_cvt_pk_bf16_f32 v99, v128, v129
	v_pk_mul_f32 v[128:129], v[120:121], s[48:49] op_sel_hi:[1,0]
	v_pk_fma_f32 v[116:117], v[116:117], v[148:149], v[160:161]
	v_med3_f32 v128, v128, s97, v211
	v_med3_f32 v129, v129, s97, v211
	v_pk_mul_f32 v[138:139], v[128:129], v[128:129]
	v_pk_mul_f32 v[90:91], v[90:91], v[184:185] op_sel_hi:[1,0]
	v_pk_fma_f32 v[146:147], v[138:139], s[60:61], v[114:115] op_sel_hi:[1,0,0] neg_lo:[1,0,0] neg_hi:[1,0,0]
	v_pk_fma_f32 v[142:143], v[138:139], s[52:53], v[106:107] op_sel_hi:[1,0,0]
	v_pk_fma_f32 v[146:147], v[138:139], v[146:147], s[62:63] op_sel_hi:[1,1,0]
	v_pk_fma_f32 v[142:143], v[138:139], v[142:143], s[54:55] op_sel_hi:[1,1,0]
	v_pk_fma_f32 v[146:147], v[138:139], v[146:147], s[66:67] op_sel_hi:[1,1,0]
	v_pk_fma_f32 v[142:143], v[138:139], v[142:143], s[56:57] op_sel_hi:[1,1,0]
	v_pk_fma_f32 v[146:147], v[138:139], v[146:147], s[72:73] op_sel_hi:[1,1,0]
	v_pk_fma_f32 v[116:117], v[104:105], v[152:153], v[116:117]
	v_pk_fma_f32 v[146:147], v[138:139], v[146:147], s[74:75] op_sel_hi:[1,1,0]
	v_pk_mul_f32 v[120:121], v[120:121], 0.5 op_sel_hi:[1,0]
	v_pk_fma_f32 v[146:147], v[138:139], v[146:147], 1.0 op_sel_hi:[1,1,0]
	v_pk_fma_f32 v[138:139], v[138:139], v[142:143], s[58:59] op_sel_hi:[1,1,0]
	v_rcp_f32_e32 v146, v146
	v_rcp_f32_e32 v147, v147
	v_pk_mul_f32 v[128:129], v[128:129], v[138:139]
	v_pk_fma_f32 v[112:113], v[132:133], v[112:113], v[144:145]
	v_pk_fma_f32 v[116:117], v[90:91], v[156:157], v[116:117]
	v_pk_mul_f32 v[128:129], v[128:129], v[146:147]
	v_pk_mul_f32 v[86:87], v[86:87], v[182:183] op_sel_hi:[1,0]
	v_pk_fma_f32 v[120:121], v[120:121], v[128:129], v[120:121]
	v_pk_fma_f32 v[112:113], v[136:137], v[96:97], v[112:113]
	v_pk_mul_f32 v[116:117], v[116:117], v[120:121]
	v_pk_fma_f32 v[112:113], v[140:141], v[86:87], v[112:113]
	v_cndmask_b32_e64 v109, v89, 0, s[0:1]
	v_cvt_pk_bf16_f32 v89, v116, v117
	v_pk_mul_f32 v[116:117], v[112:113], s[48:49] op_sel_hi:[1,0]
	v_pk_fma_f32 v[104:105], v[104:105], v[148:149], v[160:161]
	v_med3_f32 v116, v116, s97, v211
	v_med3_f32 v117, v117, s97, v211
	v_pk_mul_f32 v[120:121], v[116:117], v[116:117]
	v_pk_mul_f32 v[82:83], v[82:83], v[182:183] op_sel_hi:[1,0]
	v_pk_fma_f32 v[138:139], v[120:121], s[60:61], v[114:115] op_sel_hi:[1,0,0] neg_lo:[1,0,0] neg_hi:[1,0,0]
	v_pk_fma_f32 v[128:129], v[120:121], s[52:53], v[106:107] op_sel_hi:[1,0,0]
	v_pk_fma_f32 v[138:139], v[120:121], v[138:139], s[62:63] op_sel_hi:[1,1,0]
	v_pk_fma_f32 v[128:129], v[120:121], v[128:129], s[54:55] op_sel_hi:[1,1,0]
	v_pk_fma_f32 v[138:139], v[120:121], v[138:139], s[66:67] op_sel_hi:[1,1,0]
	v_pk_fma_f32 v[128:129], v[120:121], v[128:129], s[56:57] op_sel_hi:[1,1,0]
	v_pk_fma_f32 v[138:139], v[120:121], v[138:139], s[72:73] op_sel_hi:[1,1,0]
	v_pk_fma_f32 v[104:105], v[90:91], v[152:153], v[104:105]
	v_pk_fma_f32 v[138:139], v[120:121], v[138:139], s[74:75] op_sel_hi:[1,1,0]
	v_pk_mul_f32 v[112:113], v[112:113], 0.5 op_sel_hi:[1,0]
	v_pk_fma_f32 v[138:139], v[120:121], v[138:139], 1.0 op_sel_hi:[1,1,0]
	v_pk_fma_f32 v[120:121], v[120:121], v[128:129], s[58:59] op_sel_hi:[1,1,0]
	v_rcp_f32_e32 v138, v138
	v_rcp_f32_e32 v139, v139
	v_pk_mul_f32 v[116:117], v[116:117], v[120:121]
	v_pk_fma_f32 v[96:97], v[132:133], v[96:97], v[144:145]
	v_pk_fma_f32 v[104:105], v[82:83], v[156:157], v[104:105]
	v_pk_mul_f32 v[116:117], v[116:117], v[138:139]
	v_pk_mul_f32 v[78:79], v[78:79], v[180:181] op_sel_hi:[1,0]
	v_pk_fma_f32 v[112:113], v[112:113], v[116:117], v[112:113]
	v_pk_fma_f32 v[96:97], v[136:137], v[86:87], v[96:97]
	v_pk_mul_f32 v[104:105], v[104:105], v[112:113]
	v_pk_fma_f32 v[96:97], v[140:141], v[78:79], v[96:97]
	v_cndmask_b32_e64 v108, v81, 0, s[0:1]
	v_cvt_pk_bf16_f32 v81, v104, v105
	v_pk_mul_f32 v[104:105], v[96:97], s[48:49] op_sel_hi:[1,0]
	v_pk_fma_f32 v[90:91], v[90:91], v[148:149], v[160:161]
	v_med3_f32 v104, v104, s97, v211
	v_med3_f32 v105, v105, s97, v211
	v_pk_mul_f32 v[112:113], v[104:105], v[104:105]
	v_pk_mul_f32 v[74:75], v[74:75], v[180:181] op_sel_hi:[1,0]
	v_pk_fma_f32 v[120:121], v[112:113], s[60:61], v[114:115] op_sel_hi:[1,0,0] neg_lo:[1,0,0] neg_hi:[1,0,0]
	v_pk_fma_f32 v[116:117], v[112:113], s[52:53], v[106:107] op_sel_hi:[1,0,0]
	v_pk_fma_f32 v[120:121], v[112:113], v[120:121], s[62:63] op_sel_hi:[1,1,0]
	v_pk_fma_f32 v[116:117], v[112:113], v[116:117], s[54:55] op_sel_hi:[1,1,0]
	v_pk_fma_f32 v[120:121], v[112:113], v[120:121], s[66:67] op_sel_hi:[1,1,0]
	v_pk_fma_f32 v[116:117], v[112:113], v[116:117], s[56:57] op_sel_hi:[1,1,0]
	v_pk_fma_f32 v[120:121], v[112:113], v[120:121], s[72:73] op_sel_hi:[1,1,0]
	v_pk_fma_f32 v[90:91], v[82:83], v[152:153], v[90:91]
	v_pk_fma_f32 v[120:121], v[112:113], v[120:121], s[74:75] op_sel_hi:[1,1,0]
	v_pk_mul_f32 v[96:97], v[96:97], 0.5 op_sel_hi:[1,0]
	v_pk_fma_f32 v[120:121], v[112:113], v[120:121], 1.0 op_sel_hi:[1,1,0]
	v_pk_fma_f32 v[112:113], v[112:113], v[116:117], s[58:59] op_sel_hi:[1,1,0]
	v_rcp_f32_e32 v120, v120
	v_rcp_f32_e32 v121, v121
	v_pk_mul_f32 v[104:105], v[104:105], v[112:113]
	v_pk_fma_f32 v[86:87], v[132:133], v[86:87], v[144:145]
	v_pk_fma_f32 v[90:91], v[74:75], v[156:157], v[90:91]
	v_pk_mul_f32 v[104:105], v[104:105], v[120:121]
	v_pk_mul_f32 v[70:71], v[70:71], v[178:179] op_sel_hi:[1,0]
	v_pk_fma_f32 v[96:97], v[96:97], v[104:105], v[96:97]
	v_pk_fma_f32 v[86:87], v[136:137], v[78:79], v[86:87]
	v_pk_mul_f32 v[90:91], v[90:91], v[96:97]
	v_pk_fma_f32 v[86:87], v[140:141], v[70:71], v[86:87]
	v_cvt_pk_bf16_f32 v73, v90, v91
	v_pk_fma_f32 v[82:83], v[82:83], v[148:149], v[160:161]
	v_pk_mul_f32 v[90:91], v[86:87], s[48:49] op_sel_hi:[1,0]
	v_pk_mul_f32 v[66:67], v[66:67], v[178:179] op_sel_hi:[1,0]
	v_med3_f32 v90, v90, s97, v211
	v_med3_f32 v91, v91, s97, v211
	v_pk_mul_f32 v[96:97], v[90:91], v[90:91]
	v_pk_fma_f32 v[82:83], v[74:75], v[152:153], v[82:83]
	v_pk_fma_f32 v[112:113], v[96:97], s[60:61], v[114:115] op_sel_hi:[1,0,0] neg_lo:[1,0,0] neg_hi:[1,0,0]
	v_pk_fma_f32 v[104:105], v[96:97], s[52:53], v[106:107] op_sel_hi:[1,0,0]
	v_pk_fma_f32 v[112:113], v[96:97], v[112:113], s[62:63] op_sel_hi:[1,1,0]
	v_pk_fma_f32 v[104:105], v[96:97], v[104:105], s[54:55] op_sel_hi:[1,1,0]
	v_pk_fma_f32 v[112:113], v[96:97], v[112:113], s[66:67] op_sel_hi:[1,1,0]
	v_pk_fma_f32 v[104:105], v[96:97], v[104:105], s[56:57] op_sel_hi:[1,1,0]
	v_pk_fma_f32 v[112:113], v[96:97], v[112:113], s[72:73] op_sel_hi:[1,1,0]
	v_pk_mul_f32 v[86:87], v[86:87], 0.5 op_sel_hi:[1,0]
	v_pk_fma_f32 v[112:113], v[96:97], v[112:113], s[74:75] op_sel_hi:[1,1,0]
	v_pk_fma_f32 v[78:79], v[132:133], v[78:79], v[144:145]
	v_pk_fma_f32 v[112:113], v[96:97], v[112:113], 1.0 op_sel_hi:[1,1,0]
	v_pk_fma_f32 v[96:97], v[96:97], v[104:105], s[58:59] op_sel_hi:[1,1,0]
	v_rcp_f32_e32 v112, v112
	v_rcp_f32_e32 v113, v113
	v_pk_mul_f32 v[90:91], v[90:91], v[96:97]
	v_pk_fma_f32 v[82:83], v[66:67], v[156:157], v[82:83]
	v_pk_fma_f32 v[78:79], v[136:137], v[70:71], v[78:79]
	v_pk_mul_f32 v[90:91], v[90:91], v[112:113]
	v_pk_fma_f32 v[78:79], v[140:141], v[94:95], v[78:79]
	v_pk_fma_f32 v[86:87], v[86:87], v[90:91], v[86:87]
	v_pk_fma_f32 v[74:75], v[74:75], v[148:149], v[160:161]
	v_pk_mul_f32 v[82:83], v[82:83], v[86:87]
	v_pk_fma_f32 v[74:75], v[66:67], v[152:153], v[74:75]
	v_cvt_pk_bf16_f32 v65, v82, v83
	v_pk_mul_f32 v[82:83], v[78:79], s[48:49] op_sel_hi:[1,0]
	v_pk_mul_f32 v[78:79], v[78:79], 0.5 op_sel_hi:[1,0]
	v_med3_f32 v82, v82, s97, v211
	v_med3_f32 v83, v83, s97, v211
	v_pk_mul_f32 v[86:87], v[82:83], v[82:83]
	v_pk_fma_f32 v[70:71], v[132:133], v[70:71], v[144:145]
	v_pk_fma_f32 v[96:97], v[86:87], s[60:61], v[114:115] op_sel_hi:[1,0,0] neg_lo:[1,0,0] neg_hi:[1,0,0]
	v_pk_fma_f32 v[90:91], v[86:87], s[52:53], v[106:107] op_sel_hi:[1,0,0]
	v_pk_fma_f32 v[96:97], v[86:87], v[96:97], s[62:63] op_sel_hi:[1,1,0]
	v_pk_fma_f32 v[90:91], v[86:87], v[90:91], s[54:55] op_sel_hi:[1,1,0]
	v_pk_fma_f32 v[96:97], v[86:87], v[96:97], s[66:67] op_sel_hi:[1,1,0]
	v_pk_fma_f32 v[90:91], v[86:87], v[90:91], s[56:57] op_sel_hi:[1,1,0]
	v_pk_fma_f32 v[96:97], v[86:87], v[96:97], s[72:73] op_sel_hi:[1,1,0]
	v_pk_fma_f32 v[74:75], v[100:101], v[156:157], v[74:75]
	v_pk_fma_f32 v[96:97], v[86:87], v[96:97], s[74:75] op_sel_hi:[1,1,0]
	v_pk_fma_f32 v[70:71], v[136:137], v[94:95], v[70:71]
	v_pk_fma_f32 v[96:97], v[86:87], v[96:97], 1.0 op_sel_hi:[1,1,0]
	v_pk_fma_f32 v[86:87], v[86:87], v[90:91], s[58:59] op_sel_hi:[1,1,0]
	v_rcp_f32_e32 v96, v96
	v_rcp_f32_e32 v97, v97
	v_pk_mul_f32 v[82:83], v[82:83], v[86:87]
	v_pk_fma_f32 v[70:71], v[140:141], v[108:109], v[70:71]
	v_pk_fma_f32 v[66:67], v[148:149], v[66:67], v[160:161]
	v_pk_mul_f32 v[82:83], v[82:83], v[96:97]
	v_pk_fma_f32 v[66:67], v[152:153], v[100:101], v[66:67]
	v_pk_fma_f32 v[78:79], v[78:79], v[82:83], v[78:79]
	v_pk_fma_f32 v[66:67], v[156:157], v[124:125], v[66:67]
	v_pk_mul_f32 v[74:75], v[74:75], v[78:79]
	s_nop 0
	v_cvt_pk_bf16_f32 v69, v74, v75
	v_pk_mul_f32 v[74:75], v[70:71], s[48:49] op_sel_hi:[1,0]
	v_pk_mul_f32 v[70:71], v[70:71], 0.5 op_sel_hi:[1,0]
	v_med3_f32 v74, v74, s97, v211
	v_med3_f32 v75, v75, s97, v211
	v_pk_mul_f32 v[78:79], v[74:75], v[74:75]
	s_nop 0
	v_pk_fma_f32 v[86:87], v[78:79], s[60:61], v[114:115] op_sel_hi:[1,0,0] neg_lo:[1,0,0] neg_hi:[1,0,0]
	v_pk_fma_f32 v[82:83], v[78:79], s[52:53], v[106:107] op_sel_hi:[1,0,0]
	v_pk_fma_f32 v[86:87], v[78:79], v[86:87], s[62:63] op_sel_hi:[1,1,0]
	v_pk_fma_f32 v[82:83], v[78:79], v[82:83], s[54:55] op_sel_hi:[1,1,0]
	v_pk_fma_f32 v[86:87], v[78:79], v[86:87], s[66:67] op_sel_hi:[1,1,0]
	v_pk_fma_f32 v[82:83], v[78:79], v[82:83], s[56:57] op_sel_hi:[1,1,0]
	v_pk_fma_f32 v[86:87], v[78:79], v[86:87], s[72:73] op_sel_hi:[1,1,0]
	s_nop 0
	v_pk_fma_f32 v[86:87], v[78:79], v[86:87], s[74:75] op_sel_hi:[1,1,0]
	s_nop 0
	v_pk_fma_f32 v[86:87], v[78:79], v[86:87], 1.0 op_sel_hi:[1,1,0]
	v_pk_fma_f32 v[78:79], v[78:79], v[82:83], s[58:59] op_sel_hi:[1,1,0]
	v_rcp_f32_e32 v86, v86
	v_rcp_f32_e32 v87, v87
	v_pk_mul_f32 v[74:75], v[74:75], v[78:79]
	s_nop 0
	v_pk_mul_f32 v[74:75], v[74:75], v[86:87]
	s_nop 0
	v_pk_fma_f32 v[70:71], v[70:71], v[74:75], v[70:71]
	s_nop 0
	v_pk_mul_f32 v[66:67], v[66:67], v[70:71]
	s_nop 0
	v_cvt_pk_bf16_f32 v77, v66, v67
	v_or_b32_e32 v66, 6, v176
	v_ashrrev_i32_e32 v67, 31, v66
	v_lshlrev_b64 v[66:67], 2, v[66:67]
	v_lshl_add_u64 v[70:71], s[36:37], 0, v[66:67]
	global_load_dwordx2 v[86:87], v[194:195], off offset:24
	v_lshl_add_u64 v[74:75], s[38:39], 0, v[66:67]
	global_load_dwordx2 v[96:97], v[196:197], off offset:24
	v_lshl_add_u64 v[78:79], s[40:41], 0, v[66:67]
	v_lshl_add_u64 v[82:83], s[42:43], 0, v[66:67]
	global_load_dwordx2 v[104:105], v[70:71], off
	global_load_dwordx2 v[108:109], v[74:75], off
	global_load_dwordx2 v[112:113], v[78:79], off
	global_load_dwordx2 v[116:117], v[82:83], off
	v_lshl_add_u64 v[70:71], s[44:45], 0, v[66:67]
	v_lshl_add_u64 v[66:67], s[46:47], 0, v[66:67]
	global_load_dwordx2 v[120:121], v[70:71], off
	global_load_dwordx2 v[124:125], v[66:67], off
	v_pk_mul_f32 v[40:41], v[40:41], v[192:193] op_sel_hi:[1,0]
	v_pk_mul_f32 v[70:71], v[56:57], v[190:191] op_sel_hi:[1,0]
	v_pk_mul_f32 v[66:67], v[60:61], v[190:191] op_sel_hi:[1,0]
	v_mov_b32_dpp v56, v40 row_shr:1 row_mask:0xf bank_mask:0xf bound_ctrl:1
	v_mov_b32_dpp v57, v41 row_shr:1 row_mask:0xf bank_mask:0xf bound_ctrl:1
	v_cndmask_b32_e64 v75, v57, 0, s[84:85]
	v_cndmask_b32_e64 v74, v56, 0, s[84:85]
	s_waitcnt vmcnt(14)
	v_pk_fma_f32 v[74:75], v[84:85], v[74:75], v[102:103]
	v_pk_mul_f32 v[52:53], v[52:53], v[188:189] op_sel_hi:[1,0]
	s_waitcnt vmcnt(13)
	v_pk_fma_f32 v[74:75], v[66:67], v[110:111], v[74:75]
	v_mov_b32_dpp v82, v66 row_shl:1 row_mask:0xf bank_mask:0xf bound_ctrl:1
	v_mov_b32_dpp v83, v67 row_shl:1 row_mask:0xf bank_mask:0xf bound_ctrl:1
	s_waitcnt vmcnt(12)
	v_pk_fma_f32 v[74:75], v[52:53], v[118:119], v[74:75]
	v_pk_mul_f32 v[32:33], v[32:33], v[192:193] op_sel_hi:[1,0]
	v_cndmask_b32_e64 v57, v83, 0, s[0:1]
	v_cndmask_b32_e64 v56, v82, 0, s[0:1]
	v_pk_mul_f32 v[82:83], v[74:75], s[48:49] op_sel_hi:[1,0]
	v_mov_b32_dpp v60, v32 row_shr:1 row_mask:0xf bank_mask:0xf bound_ctrl:1
	v_mov_b32_dpp v61, v33 row_shr:1 row_mask:0xf bank_mask:0xf bound_ctrl:1
	v_mov_b32_dpp v90, v70 row_shl:1 row_mask:0xf bank_mask:0xf bound_ctrl:1
	v_mov_b32_dpp v91, v71 row_shl:1 row_mask:0xf bank_mask:0xf bound_ctrl:1
	v_med3_f32 v82, v82, s97, v211
	v_med3_f32 v83, v83, s97, v211
	v_cndmask_b32_e64 v79, v61, 0, s[84:85]
	v_cndmask_b32_e64 v78, v60, 0, s[84:85]
	v_cndmask_b32_e64 v61, v91, 0, s[0:1]
	v_cndmask_b32_e64 v60, v90, 0, s[0:1]
	v_pk_mul_f32 v[90:91], v[82:83], v[82:83]
	s_waitcnt vmcnt(8)
	v_pk_fma_f32 v[78:79], v[122:123], v[78:79], v[134:135]
	v_pk_fma_f32 v[100:101], v[90:91], s[60:61], v[114:115] op_sel_hi:[1,0,0] neg_lo:[1,0,0] neg_hi:[1,0,0]
	v_pk_fma_f32 v[94:95], v[90:91], s[52:53], v[106:107] op_sel_hi:[1,0,0]
	v_pk_fma_f32 v[100:101], v[90:91], v[100:101], s[62:63] op_sel_hi:[1,1,0]
	v_pk_fma_f32 v[94:95], v[90:91], v[94:95], s[54:55] op_sel_hi:[1,1,0]
	v_pk_fma_f32 v[100:101], v[90:91], v[100:101], s[66:67] op_sel_hi:[1,1,0]
	v_pk_fma_f32 v[94:95], v[90:91], v[94:95], s[56:57] op_sel_hi:[1,1,0]
	v_pk_fma_f32 v[100:101], v[90:91], v[100:101], s[72:73] op_sel_hi:[1,1,0]
	v_pk_mul_f32 v[48:49], v[48:49], v[188:189] op_sel_hi:[1,0]
	v_pk_fma_f32 v[100:101], v[90:91], v[100:101], s[74:75] op_sel_hi:[1,1,0]
	v_pk_fma_f32 v[78:79], v[70:71], v[126:127], v[78:79]
	v_pk_fma_f32 v[100:101], v[90:91], v[100:101], 1.0 op_sel_hi:[1,1,0]
	v_pk_fma_f32 v[90:91], v[90:91], v[94:95], s[58:59] op_sel_hi:[1,1,0]
	v_rcp_f32_e32 v100, v100
	v_rcp_f32_e32 v101, v101
	v_pk_mul_f32 v[82:83], v[82:83], v[90:91]
	v_pk_mul_f32 v[74:75], v[74:75], 0.5 op_sel_hi:[1,0]
	v_pk_fma_f32 v[66:67], v[66:67], v[84:85], v[102:103]
	v_pk_mul_f32 v[82:83], v[82:83], v[100:101]
	v_pk_fma_f32 v[78:79], v[48:49], v[130:131], v[78:79]
	v_pk_fma_f32 v[74:75], v[74:75], v[82:83], v[74:75]
	v_pk_mul_f32 v[44:45], v[44:45], v[186:187] op_sel_hi:[1,0]
	v_pk_fma_f32 v[66:67], v[52:53], v[110:111], v[66:67]
	v_pk_mul_f32 v[74:75], v[78:79], v[74:75]
	v_pk_fma_f32 v[66:67], v[44:45], v[118:119], v[66:67]
	v_cvt_pk_bf16_f32 v94, v74, v75
	v_pk_fma_f32 v[70:71], v[70:71], v[122:123], v[134:135]
	v_pk_mul_f32 v[74:75], v[66:67], s[48:49] op_sel_hi:[1,0]
	v_pk_mul_f32 v[36:37], v[36:37], v[186:187] op_sel_hi:[1,0]
	v_med3_f32 v74, v74, s97, v211
	v_med3_f32 v75, v75, s97, v211
	v_pk_mul_f32 v[78:79], v[74:75], v[74:75]
	v_pk_fma_f32 v[70:71], v[48:49], v[126:127], v[70:71]
	v_pk_fma_f32 v[90:91], v[78:79], s[60:61], v[114:115] op_sel_hi:[1,0,0] neg_lo:[1,0,0] neg_hi:[1,0,0]
	v_pk_fma_f32 v[82:83], v[78:79], s[52:53], v[106:107] op_sel_hi:[1,0,0]
	v_pk_fma_f32 v[90:91], v[78:79], v[90:91], s[62:63] op_sel_hi:[1,1,0]
	v_pk_fma_f32 v[82:83], v[78:79], v[82:83], s[54:55] op_sel_hi:[1,1,0]
	v_pk_fma_f32 v[90:91], v[78:79], v[90:91], s[66:67] op_sel_hi:[1,1,0]
	v_pk_fma_f32 v[82:83], v[78:79], v[82:83], s[56:57] op_sel_hi:[1,1,0]
	v_pk_fma_f32 v[90:91], v[78:79], v[90:91], s[72:73] op_sel_hi:[1,1,0]
	v_pk_mul_f32 v[66:67], v[66:67], 0.5 op_sel_hi:[1,0]
	v_pk_fma_f32 v[90:91], v[78:79], v[90:91], s[74:75] op_sel_hi:[1,1,0]
	v_pk_fma_f32 v[52:53], v[52:53], v[84:85], v[102:103]
	v_pk_fma_f32 v[90:91], v[78:79], v[90:91], 1.0 op_sel_hi:[1,1,0]
	v_pk_fma_f32 v[78:79], v[78:79], v[82:83], s[58:59] op_sel_hi:[1,1,0]
	v_rcp_f32_e32 v90, v90
	v_rcp_f32_e32 v91, v91
	v_pk_mul_f32 v[74:75], v[74:75], v[78:79]
	v_pk_fma_f32 v[70:71], v[36:37], v[130:131], v[70:71]
	v_pk_mul_f32 v[28:29], v[28:29], v[184:185] op_sel_hi:[1,0]
	v_pk_mul_f32 v[74:75], v[74:75], v[90:91]
	v_pk_fma_f32 v[52:53], v[44:45], v[110:111], v[52:53]
	v_pk_fma_f32 v[66:67], v[66:67], v[74:75], v[66:67]
	v_pk_fma_f32 v[52:53], v[28:29], v[118:119], v[52:53]
	v_pk_mul_f32 v[66:67], v[70:71], v[66:67]
	v_pk_fma_f32 v[48:49], v[48:49], v[122:123], v[134:135]
	v_cvt_pk_bf16_f32 v100, v66, v67
	v_pk_mul_f32 v[66:67], v[52:53], s[48:49] op_sel_hi:[1,0]
	v_pk_mul_f32 v[24:25], v[24:25], v[184:185] op_sel_hi:[1,0]
	v_med3_f32 v66, v66, s97, v211
	v_med3_f32 v67, v67, s97, v211
	v_pk_mul_f32 v[70:71], v[66:67], v[66:67]
	v_pk_fma_f32 v[48:49], v[36:37], v[126:127], v[48:49]
	v_pk_fma_f32 v[78:79], v[70:71], s[60:61], v[114:115] op_sel_hi:[1,0,0] neg_lo:[1,0,0] neg_hi:[1,0,0]
	v_pk_fma_f32 v[74:75], v[70:71], s[52:53], v[106:107] op_sel_hi:[1,0,0]
	v_pk_fma_f32 v[78:79], v[70:71], v[78:79], s[62:63] op_sel_hi:[1,1,0]
	v_pk_fma_f32 v[74:75], v[70:71], v[74:75], s[54:55] op_sel_hi:[1,1,0]
	v_pk_fma_f32 v[78:79], v[70:71], v[78:79], s[66:67] op_sel_hi:[1,1,0]
	v_pk_fma_f32 v[74:75], v[70:71], v[74:75], s[56:57] op_sel_hi:[1,1,0]
	v_pk_fma_f32 v[78:79], v[70:71], v[78:79], s[72:73] op_sel_hi:[1,1,0]
	v_pk_mul_f32 v[52:53], v[52:53], 0.5 op_sel_hi:[1,0]
	v_pk_fma_f32 v[78:79], v[70:71], v[78:79], s[74:75] op_sel_hi:[1,1,0]
	v_pk_fma_f32 v[44:45], v[44:45], v[84:85], v[102:103]
	v_pk_fma_f32 v[78:79], v[70:71], v[78:79], 1.0 op_sel_hi:[1,1,0]
	v_pk_fma_f32 v[70:71], v[70:71], v[74:75], s[58:59] op_sel_hi:[1,1,0]
	v_rcp_f32_e32 v78, v78
	v_rcp_f32_e32 v79, v79
	v_pk_mul_f32 v[66:67], v[66:67], v[70:71]
	v_pk_fma_f32 v[48:49], v[24:25], v[130:131], v[48:49]
	v_pk_mul_f32 v[20:21], v[20:21], v[182:183] op_sel_hi:[1,0]
	v_pk_mul_f32 v[66:67], v[66:67], v[78:79]
	v_pk_fma_f32 v[44:45], v[28:29], v[110:111], v[44:45]
	v_pk_fma_f32 v[52:53], v[52:53], v[66:67], v[52:53]
	v_pk_fma_f32 v[44:45], v[20:21], v[118:119], v[44:45]
	v_pk_mul_f32 v[48:49], v[48:49], v[52:53]
	v_pk_fma_f32 v[36:37], v[36:37], v[122:123], v[134:135]
	v_cvt_pk_bf16_f32 v90, v48, v49
	v_pk_mul_f32 v[48:49], v[44:45], s[48:49] op_sel_hi:[1,0]
	v_pk_mul_f32 v[16:17], v[16:17], v[182:183] op_sel_hi:[1,0]
	v_med3_f32 v48, v48, s97, v211
	v_med3_f32 v49, v49, s97, v211
	v_pk_mul_f32 v[52:53], v[48:49], v[48:49]
	v_pk_fma_f32 v[36:37], v[24:25], v[126:127], v[36:37]
	v_pk_fma_f32 v[70:71], v[52:53], s[60:61], v[114:115] op_sel_hi:[1,0,0] neg_lo:[1,0,0] neg_hi:[1,0,0]
	v_pk_fma_f32 v[66:67], v[52:53], s[52:53], v[106:107] op_sel_hi:[1,0,0]
	v_pk_fma_f32 v[70:71], v[52:53], v[70:71], s[62:63] op_sel_hi:[1,1,0]
	v_pk_fma_f32 v[66:67], v[52:53], v[66:67], s[54:55] op_sel_hi:[1,1,0]
	v_pk_fma_f32 v[70:71], v[52:53], v[70:71], s[66:67] op_sel_hi:[1,1,0]
	v_pk_fma_f32 v[66:67], v[52:53], v[66:67], s[56:57] op_sel_hi:[1,1,0]
	v_pk_fma_f32 v[70:71], v[52:53], v[70:71], s[72:73] op_sel_hi:[1,1,0]
	v_pk_mul_f32 v[44:45], v[44:45], 0.5 op_sel_hi:[1,0]
	v_pk_fma_f32 v[70:71], v[52:53], v[70:71], s[74:75] op_sel_hi:[1,1,0]
	v_pk_fma_f32 v[28:29], v[28:29], v[84:85], v[102:103]
	v_pk_fma_f32 v[70:71], v[52:53], v[70:71], 1.0 op_sel_hi:[1,1,0]
	v_pk_fma_f32 v[52:53], v[52:53], v[66:67], s[58:59] op_sel_hi:[1,1,0]
	v_rcp_f32_e32 v70, v70
	v_rcp_f32_e32 v71, v71
	v_pk_mul_f32 v[48:49], v[48:49], v[52:53]
	v_pk_fma_f32 v[36:37], v[16:17], v[130:131], v[36:37]
	v_pk_mul_f32 v[12:13], v[12:13], v[180:181] op_sel_hi:[1,0]
	v_pk_mul_f32 v[48:49], v[48:49], v[70:71]
	v_pk_fma_f32 v[28:29], v[20:21], v[110:111], v[28:29]
	v_pk_fma_f32 v[44:45], v[44:45], v[48:49], v[44:45]
	v_pk_fma_f32 v[28:29], v[12:13], v[118:119], v[28:29]
	v_pk_mul_f32 v[36:37], v[36:37], v[44:45]
	v_pk_fma_f32 v[24:25], v[24:25], v[122:123], v[134:135]
	v_cvt_pk_bf16_f32 v82, v36, v37
	v_pk_mul_f32 v[36:37], v[28:29], s[48:49] op_sel_hi:[1,0]
	v_pk_mul_f32 v[8:9], v[8:9], v[180:181] op_sel_hi:[1,0]
	v_med3_f32 v36, v36, s97, v211
	v_med3_f32 v37, v37, s97, v211
	v_pk_mul_f32 v[44:45], v[36:37], v[36:37]
	v_pk_fma_f32 v[24:25], v[16:17], v[126:127], v[24:25]
	v_pk_fma_f32 v[52:53], v[44:45], s[60:61], v[114:115] op_sel_hi:[1,0,0] neg_lo:[1,0,0] neg_hi:[1,0,0]
	v_pk_fma_f32 v[48:49], v[44:45], s[52:53], v[106:107] op_sel_hi:[1,0,0]
	v_pk_fma_f32 v[52:53], v[44:45], v[52:53], s[62:63] op_sel_hi:[1,1,0]
	v_pk_fma_f32 v[48:49], v[44:45], v[48:49], s[54:55] op_sel_hi:[1,1,0]
	v_pk_fma_f32 v[52:53], v[44:45], v[52:53], s[66:67] op_sel_hi:[1,1,0]
	v_pk_fma_f32 v[48:49], v[44:45], v[48:49], s[56:57] op_sel_hi:[1,1,0]
	v_pk_fma_f32 v[52:53], v[44:45], v[52:53], s[72:73] op_sel_hi:[1,1,0]
	v_pk_mul_f32 v[28:29], v[28:29], 0.5 op_sel_hi:[1,0]
	v_pk_fma_f32 v[52:53], v[44:45], v[52:53], s[74:75] op_sel_hi:[1,1,0]
	v_pk_fma_f32 v[20:21], v[20:21], v[84:85], v[102:103]
	v_pk_fma_f32 v[52:53], v[44:45], v[52:53], 1.0 op_sel_hi:[1,1,0]
	v_pk_fma_f32 v[44:45], v[44:45], v[48:49], s[58:59] op_sel_hi:[1,1,0]
	v_rcp_f32_e32 v52, v52
	v_rcp_f32_e32 v53, v53
	v_pk_mul_f32 v[36:37], v[36:37], v[44:45]
	v_pk_fma_f32 v[24:25], v[8:9], v[130:131], v[24:25]
	v_pk_mul_f32 v[4:5], v[4:5], v[178:179] op_sel_hi:[1,0]
	v_pk_mul_f32 v[36:37], v[36:37], v[52:53]
	v_pk_fma_f32 v[20:21], v[12:13], v[110:111], v[20:21]
	v_pk_fma_f32 v[28:29], v[28:29], v[36:37], v[28:29]
	v_pk_fma_f32 v[20:21], v[4:5], v[118:119], v[20:21]
	v_pk_mul_f32 v[24:25], v[24:25], v[28:29]
	v_pk_fma_f32 v[16:17], v[16:17], v[122:123], v[134:135]
	v_cvt_pk_bf16_f32 v74, v24, v25
	v_pk_mul_f32 v[24:25], v[20:21], s[48:49] op_sel_hi:[1,0]
	v_pk_mul_f32 v[0:1], v[0:1], v[178:179] op_sel_hi:[1,0]
	v_med3_f32 v24, v24, s97, v211
	v_med3_f32 v25, v25, s97, v211
	v_pk_mul_f32 v[28:29], v[24:25], v[24:25]
	v_pk_fma_f32 v[16:17], v[8:9], v[126:127], v[16:17]
	v_pk_fma_f32 v[44:45], v[28:29], s[60:61], v[114:115] op_sel_hi:[1,0,0] neg_lo:[1,0,0] neg_hi:[1,0,0]
	v_pk_fma_f32 v[36:37], v[28:29], s[52:53], v[106:107] op_sel_hi:[1,0,0]
	v_pk_fma_f32 v[44:45], v[28:29], v[44:45], s[62:63] op_sel_hi:[1,1,0]
	v_pk_fma_f32 v[36:37], v[28:29], v[36:37], s[54:55] op_sel_hi:[1,1,0]
	v_pk_fma_f32 v[44:45], v[28:29], v[44:45], s[66:67] op_sel_hi:[1,1,0]
	v_pk_fma_f32 v[36:37], v[28:29], v[36:37], s[56:57] op_sel_hi:[1,1,0]
	v_pk_fma_f32 v[44:45], v[28:29], v[44:45], s[72:73] op_sel_hi:[1,1,0]
	v_pk_mul_f32 v[20:21], v[20:21], 0.5 op_sel_hi:[1,0]
	v_pk_fma_f32 v[44:45], v[28:29], v[44:45], s[74:75] op_sel_hi:[1,1,0]
	v_pk_fma_f32 v[12:13], v[12:13], v[84:85], v[102:103]
	v_pk_fma_f32 v[44:45], v[28:29], v[44:45], 1.0 op_sel_hi:[1,1,0]
	v_pk_fma_f32 v[28:29], v[28:29], v[36:37], s[58:59] op_sel_hi:[1,1,0]
	v_rcp_f32_e32 v44, v44
	v_rcp_f32_e32 v45, v45
	v_pk_mul_f32 v[24:25], v[24:25], v[28:29]
	v_pk_fma_f32 v[16:17], v[0:1], v[130:131], v[16:17]
	v_pk_fma_f32 v[12:13], v[4:5], v[110:111], v[12:13]
	v_pk_mul_f32 v[24:25], v[24:25], v[44:45]
	v_pk_fma_f32 v[12:13], v[40:41], v[118:119], v[12:13]
	v_pk_fma_f32 v[20:21], v[20:21], v[24:25], v[20:21]
	v_pk_fma_f32 v[8:9], v[8:9], v[122:123], v[134:135]
	v_pk_mul_f32 v[16:17], v[16:17], v[20:21]
	v_pk_fma_f32 v[8:9], v[0:1], v[126:127], v[8:9]
	v_cvt_pk_bf16_f32 v66, v16, v17
	v_pk_mul_f32 v[16:17], v[12:13], s[48:49] op_sel_hi:[1,0]
	v_pk_mul_f32 v[12:13], v[12:13], 0.5 op_sel_hi:[1,0]
	v_med3_f32 v16, v16, s97, v211
	v_med3_f32 v17, v17, s97, v211
	v_pk_mul_f32 v[20:21], v[16:17], v[16:17]
	v_pk_fma_f32 v[4:5], v[4:5], v[84:85], v[102:103]
	v_pk_fma_f32 v[28:29], v[20:21], s[60:61], v[114:115] op_sel_hi:[1,0,0] neg_lo:[1,0,0] neg_hi:[1,0,0]
	v_pk_fma_f32 v[24:25], v[20:21], s[52:53], v[106:107] op_sel_hi:[1,0,0]
	v_pk_fma_f32 v[28:29], v[20:21], v[28:29], s[62:63] op_sel_hi:[1,1,0]
	v_pk_fma_f32 v[24:25], v[20:21], v[24:25], s[54:55] op_sel_hi:[1,1,0]
	v_pk_fma_f32 v[28:29], v[20:21], v[28:29], s[66:67] op_sel_hi:[1,1,0]
	v_pk_fma_f32 v[24:25], v[20:21], v[24:25], s[56:57] op_sel_hi:[1,1,0]
	v_pk_fma_f32 v[28:29], v[20:21], v[28:29], s[72:73] op_sel_hi:[1,1,0]
	v_pk_fma_f32 v[8:9], v[32:33], v[130:131], v[8:9]
	v_pk_fma_f32 v[28:29], v[20:21], v[28:29], s[74:75] op_sel_hi:[1,1,0]
	v_pk_fma_f32 v[4:5], v[40:41], v[110:111], v[4:5]
	v_pk_fma_f32 v[28:29], v[20:21], v[28:29], 1.0 op_sel_hi:[1,1,0]
	v_pk_fma_f32 v[20:21], v[20:21], v[24:25], s[58:59] op_sel_hi:[1,1,0]
	v_rcp_f32_e32 v28, v28
	v_rcp_f32_e32 v29, v29
	v_pk_mul_f32 v[16:17], v[16:17], v[20:21]
	v_pk_fma_f32 v[4:5], v[118:119], v[56:57], v[4:5]
	v_pk_fma_f32 v[0:1], v[0:1], v[122:123], v[134:135]
	v_pk_mul_f32 v[16:17], v[16:17], v[28:29]
	v_pk_fma_f32 v[0:1], v[32:33], v[126:127], v[0:1]
	v_pk_fma_f32 v[12:13], v[12:13], v[16:17], v[12:13]
	v_pk_fma_f32 v[0:1], v[130:131], v[60:61], v[0:1]
	v_pk_mul_f32 v[8:9], v[8:9], v[12:13]
	s_nop 0
	v_cvt_pk_bf16_f32 v70, v8, v9
	v_pk_mul_f32 v[8:9], v[4:5], s[48:49] op_sel_hi:[1,0]
	v_pk_mul_f32 v[4:5], v[4:5], 0.5 op_sel_hi:[1,0]
	v_med3_f32 v8, v8, s97, v211
	v_med3_f32 v9, v9, s97, v211
	v_pk_mul_f32 v[12:13], v[8:9], v[8:9]
	s_nop 0
	v_pk_fma_f32 v[20:21], v[12:13], s[60:61], v[114:115] op_sel_hi:[1,0,0] neg_lo:[1,0,0] neg_hi:[1,0,0]
	v_pk_fma_f32 v[16:17], v[12:13], s[52:53], v[106:107] op_sel_hi:[1,0,0]
	v_pk_fma_f32 v[20:21], v[12:13], v[20:21], s[62:63] op_sel_hi:[1,1,0]
	v_pk_fma_f32 v[16:17], v[12:13], v[16:17], s[54:55] op_sel_hi:[1,1,0]
	v_pk_fma_f32 v[20:21], v[12:13], v[20:21], s[66:67] op_sel_hi:[1,1,0]
	v_pk_fma_f32 v[16:17], v[12:13], v[16:17], s[56:57] op_sel_hi:[1,1,0]
	v_pk_fma_f32 v[20:21], v[12:13], v[20:21], s[72:73] op_sel_hi:[1,1,0]
	s_nop 0
	v_pk_fma_f32 v[20:21], v[12:13], v[20:21], s[74:75] op_sel_hi:[1,1,0]
	s_nop 0
	v_pk_fma_f32 v[20:21], v[12:13], v[20:21], 1.0 op_sel_hi:[1,1,0]
	v_pk_fma_f32 v[12:13], v[12:13], v[16:17], s[58:59] op_sel_hi:[1,1,0]
	v_rcp_f32_e32 v20, v20
	v_rcp_f32_e32 v21, v21
	v_pk_mul_f32 v[8:9], v[8:9], v[12:13]
	s_nop 0
	v_pk_mul_f32 v[8:9], v[8:9], v[20:21]
	s_nop 0
	v_pk_fma_f32 v[4:5], v[4:5], v[8:9], v[4:5]
	s_nop 0
	v_pk_mul_f32 v[0:1], v[0:1], v[4:5]
	s_nop 0
	v_cvt_pk_bf16_f32 v78, v0, v1
	v_pk_mul_f32 v[0:1], v[42:43], v[192:193] op_sel_hi:[1,0]
	v_pk_mul_f32 v[16:17], v[62:63], v[190:191] op_sel_hi:[1,0]
	v_pk_mul_f32 v[4:5], v[34:35], v[192:193] op_sel_hi:[1,0]
	v_mov_b32_dpp v8, v0 row_shr:1 row_mask:0xf bank_mask:0xf bound_ctrl:1
	v_mov_b32_dpp v9, v1 row_shr:1 row_mask:0xf bank_mask:0xf bound_ctrl:1
	v_cndmask_b32_e64 v25, v9, 0, s[84:85]
	v_cndmask_b32_e64 v24, v8, 0, s[84:85]
	v_mov_b32_dpp v32, v16 row_shl:1 row_mask:0xf bank_mask:0xf bound_ctrl:1
	v_mov_b32_dpp v33, v17 row_shl:1 row_mask:0xf bank_mask:0xf bound_ctrl:1
	s_waitcnt vmcnt(6)
	v_pk_fma_f32 v[24:25], v[86:87], v[24:25], v[96:97]
	v_cndmask_b32_e64 v9, v33, 0, s[0:1]
	v_cndmask_b32_e64 v8, v32, 0, s[0:1]
	v_pk_mul_f32 v[32:33], v[54:55], v[188:189] op_sel_hi:[1,0]
	s_waitcnt vmcnt(5)
	v_pk_fma_f32 v[24:25], v[16:17], v[104:105], v[24:25]
	v_mov_b32_dpp v12, v4 row_shr:1 row_mask:0xf bank_mask:0xf bound_ctrl:1
	s_waitcnt vmcnt(4)
	v_pk_fma_f32 v[24:25], v[32:33], v[108:109], v[24:25]
	v_mov_b32_dpp v13, v5 row_shr:1 row_mask:0xf bank_mask:0xf bound_ctrl:1
	v_pk_mul_f32 v[36:37], v[24:25], s[48:49] op_sel_hi:[1,0]
	v_pk_mul_f32 v[20:21], v[58:59], v[190:191] op_sel_hi:[1,0]
	v_med3_f32 v36, v36, s97, v211
	v_med3_f32 v37, v37, s97, v211
	v_pk_mul_f32 v[40:41], v[36:37], v[36:37]
	v_cndmask_b32_e64 v29, v13, 0, s[84:85]
	v_pk_fma_f32 v[44:45], v[40:41], s[60:61], v[114:115] op_sel_hi:[1,0,0] neg_lo:[1,0,0] neg_hi:[1,0,0]
	v_pk_fma_f32 v[42:43], v[40:41], s[52:53], v[106:107] op_sel_hi:[1,0,0]
	v_pk_fma_f32 v[44:45], v[40:41], v[44:45], s[62:63] op_sel_hi:[1,1,0]
	v_pk_fma_f32 v[42:43], v[40:41], v[42:43], s[54:55] op_sel_hi:[1,1,0]
	v_pk_fma_f32 v[44:45], v[40:41], v[44:45], s[66:67] op_sel_hi:[1,1,0]
	v_pk_fma_f32 v[42:43], v[40:41], v[42:43], s[56:57] op_sel_hi:[1,1,0]
	v_pk_fma_f32 v[44:45], v[40:41], v[44:45], s[72:73] op_sel_hi:[1,1,0]
	v_cndmask_b32_e64 v28, v12, 0, s[84:85]
	v_pk_fma_f32 v[44:45], v[40:41], v[44:45], s[74:75] op_sel_hi:[1,1,0]
	v_mov_b32_dpp v34, v20 row_shl:1 row_mask:0xf bank_mask:0xf bound_ctrl:1
	v_pk_fma_f32 v[44:45], v[40:41], v[44:45], 1.0 op_sel_hi:[1,1,0]
	v_pk_fma_f32 v[40:41], v[40:41], v[42:43], s[58:59] op_sel_hi:[1,1,0]
	v_rcp_f32_e32 v44, v44
	v_rcp_f32_e32 v45, v45
	v_mov_b32_dpp v35, v21 row_shl:1 row_mask:0xf bank_mask:0xf bound_ctrl:1
	s_waitcnt vmcnt(0)
	v_pk_fma_f32 v[28:29], v[112:113], v[28:29], v[124:125]
	v_pk_mul_f32 v[36:37], v[36:37], v[40:41]
	v_cndmask_b32_e64 v13, v35, 0, s[0:1]
	v_cndmask_b32_e64 v12, v34, 0, s[0:1]
	v_pk_mul_f32 v[34:35], v[50:51], v[188:189] op_sel_hi:[1,0]
	v_pk_fma_f32 v[28:29], v[20:21], v[116:117], v[28:29]
	v_pk_mul_f32 v[36:37], v[36:37], v[44:45]
	v_pk_mul_f32 v[24:25], v[24:25], 0.5 op_sel_hi:[1,0]
	v_pk_fma_f32 v[28:29], v[34:35], v[120:121], v[28:29]
	v_pk_fma_f32 v[24:25], v[24:25], v[36:37], v[24:25]
	v_pk_fma_f32 v[16:17], v[16:17], v[86:87], v[96:97]
	v_pk_mul_f32 v[24:25], v[28:29], v[24:25]
	v_pk_fma_f32 v[16:17], v[32:33], v[104:105], v[16:17]
	v_cvt_pk_bf16_f32 v95, v24, v25
	v_pk_mul_f32 v[24:25], v[46:47], v[186:187] op_sel_hi:[1,0]
	v_pk_mul_f32 v[28:29], v[38:39], v[186:187] op_sel_hi:[1,0]
	v_pk_fma_f32 v[16:17], v[24:25], v[108:109], v[16:17]
	v_pk_fma_f32 v[20:21], v[20:21], v[112:113], v[124:125]
	v_pk_mul_f32 v[36:37], v[16:17], s[48:49] op_sel_hi:[1,0]
	v_pk_fma_f32 v[20:21], v[34:35], v[116:117], v[20:21]
	v_med3_f32 v36, v36, s97, v211
	v_med3_f32 v37, v37, s97, v211
	v_pk_mul_f32 v[38:39], v[36:37], v[36:37]
	v_pk_mul_f32 v[16:17], v[16:17], 0.5 op_sel_hi:[1,0]
	v_pk_fma_f32 v[42:43], v[38:39], s[60:61], v[114:115] op_sel_hi:[1,0,0] neg_lo:[1,0,0] neg_hi:[1,0,0]
	v_pk_fma_f32 v[40:41], v[38:39], s[52:53], v[106:107] op_sel_hi:[1,0,0]
	v_pk_fma_f32 v[42:43], v[38:39], v[42:43], s[62:63] op_sel_hi:[1,1,0]
	v_pk_fma_f32 v[40:41], v[38:39], v[40:41], s[54:55] op_sel_hi:[1,1,0]
	v_pk_fma_f32 v[42:43], v[38:39], v[42:43], s[66:67] op_sel_hi:[1,1,0]
	v_pk_fma_f32 v[40:41], v[38:39], v[40:41], s[56:57] op_sel_hi:[1,1,0]
	v_pk_fma_f32 v[42:43], v[38:39], v[42:43], s[72:73] op_sel_hi:[1,1,0]
	v_pk_fma_f32 v[20:21], v[28:29], v[120:121], v[20:21]
	v_pk_fma_f32 v[42:43], v[38:39], v[42:43], s[74:75] op_sel_hi:[1,1,0]
	v_pk_mul_f32 v[22:23], v[22:23], v[182:183] op_sel_hi:[1,0]
	v_pk_fma_f32 v[42:43], v[38:39], v[42:43], 1.0 op_sel_hi:[1,1,0]
	v_pk_fma_f32 v[38:39], v[38:39], v[40:41], s[58:59] op_sel_hi:[1,1,0]
	v_rcp_f32_e32 v42, v42
	v_rcp_f32_e32 v43, v43
	v_pk_mul_f32 v[36:37], v[36:37], v[38:39]
	v_pk_mul_f32 v[18:19], v[18:19], v[182:183] op_sel_hi:[1,0]
	v_pk_mul_f32 v[14:15], v[14:15], v[180:181] op_sel_hi:[1,0]
	v_pk_mul_f32 v[36:37], v[36:37], v[42:43]
	v_pk_mul_f32 v[10:11], v[10:11], v[180:181] op_sel_hi:[1,0]
	v_pk_fma_f32 v[16:17], v[16:17], v[36:37], v[16:17]
	v_pk_mul_f32 v[6:7], v[6:7], v[178:179] op_sel_hi:[1,0]
	v_pk_mul_f32 v[16:17], v[20:21], v[16:17]
	v_pk_mul_f32 v[20:21], v[26:27], v[184:185] op_sel_hi:[1,0]
	v_pk_fma_f32 v[26:27], v[32:33], v[86:87], v[96:97]
	v_cvt_pk_bf16_f32 v101, v16, v17
	v_pk_mul_f32 v[16:17], v[30:31], v[184:185] op_sel_hi:[1,0]
	v_pk_fma_f32 v[26:27], v[24:25], v[104:105], v[26:27]
	v_pk_fma_f32 v[30:31], v[34:35], v[112:113], v[124:125]
	v_pk_fma_f32 v[26:27], v[16:17], v[108:109], v[26:27]
	v_pk_fma_f32 v[30:31], v[28:29], v[116:117], v[30:31]
	v_pk_mul_f32 v[32:33], v[26:27], s[48:49] op_sel_hi:[1,0]
	v_pk_mul_f32 v[26:27], v[26:27], 0.5 op_sel_hi:[1,0]
	v_med3_f32 v32, v32, s97, v211
	v_med3_f32 v33, v33, s97, v211
	v_pk_mul_f32 v[34:35], v[32:33], v[32:33]
	v_pk_fma_f32 v[24:25], v[24:25], v[86:87], v[96:97]
	v_pk_fma_f32 v[38:39], v[34:35], s[60:61], v[114:115] op_sel_hi:[1,0,0] neg_lo:[1,0,0] neg_hi:[1,0,0]
	v_pk_fma_f32 v[36:37], v[34:35], s[52:53], v[106:107] op_sel_hi:[1,0,0]
	v_pk_fma_f32 v[38:39], v[34:35], v[38:39], s[62:63] op_sel_hi:[1,1,0]
	v_pk_fma_f32 v[36:37], v[34:35], v[36:37], s[54:55] op_sel_hi:[1,1,0]
	v_pk_fma_f32 v[38:39], v[34:35], v[38:39], s[66:67] op_sel_hi:[1,1,0]
	v_pk_fma_f32 v[36:37], v[34:35], v[36:37], s[56:57] op_sel_hi:[1,1,0]
	v_pk_fma_f32 v[38:39], v[34:35], v[38:39], s[72:73] op_sel_hi:[1,1,0]
	v_pk_fma_f32 v[30:31], v[20:21], v[120:121], v[30:31]
	v_pk_fma_f32 v[38:39], v[34:35], v[38:39], s[74:75] op_sel_hi:[1,1,0]
	v_pk_fma_f32 v[24:25], v[16:17], v[104:105], v[24:25]
	v_pk_fma_f32 v[38:39], v[34:35], v[38:39], 1.0 op_sel_hi:[1,1,0]
	v_pk_fma_f32 v[34:35], v[34:35], v[36:37], s[58:59] op_sel_hi:[1,1,0]
	v_rcp_f32_e32 v38, v38
	v_rcp_f32_e32 v39, v39
	v_pk_mul_f32 v[32:33], v[32:33], v[34:35]
	v_pk_fma_f32 v[24:25], v[22:23], v[108:109], v[24:25]
	v_pk_fma_f32 v[16:17], v[16:17], v[86:87], v[96:97]
	v_pk_mul_f32 v[32:33], v[32:33], v[38:39]
	v_pk_fma_f32 v[16:17], v[22:23], v[104:105], v[16:17]
	v_pk_fma_f32 v[26:27], v[26:27], v[32:33], v[26:27]
	v_pk_fma_f32 v[16:17], v[14:15], v[108:109], v[16:17]
	v_pk_mul_f32 v[26:27], v[30:31], v[26:27]
	v_pk_mul_f32 v[2:3], v[2:3], v[178:179] op_sel_hi:[1,0]
	v_cvt_pk_bf16_f32 v91, v26, v27
	v_pk_fma_f32 v[26:27], v[28:29], v[112:113], v[124:125]
	v_pk_mul_f32 v[28:29], v[24:25], s[48:49] op_sel_hi:[1,0]
	v_pk_fma_f32 v[26:27], v[20:21], v[116:117], v[26:27]
	v_med3_f32 v28, v28, s97, v211
	v_med3_f32 v29, v29, s97, v211
	v_pk_mul_f32 v[30:31], v[28:29], v[28:29]
	v_pk_mul_f32 v[24:25], v[24:25], 0.5 op_sel_hi:[1,0]
	v_pk_fma_f32 v[34:35], v[30:31], s[60:61], v[114:115] op_sel_hi:[1,0,0] neg_lo:[1,0,0] neg_hi:[1,0,0]
	v_pk_fma_f32 v[32:33], v[30:31], s[52:53], v[106:107] op_sel_hi:[1,0,0]
	v_pk_fma_f32 v[34:35], v[30:31], v[34:35], s[62:63] op_sel_hi:[1,1,0]
	v_pk_fma_f32 v[32:33], v[30:31], v[32:33], s[54:55] op_sel_hi:[1,1,0]
	v_pk_fma_f32 v[34:35], v[30:31], v[34:35], s[66:67] op_sel_hi:[1,1,0]
	v_pk_fma_f32 v[32:33], v[30:31], v[32:33], s[56:57] op_sel_hi:[1,1,0]
	v_pk_fma_f32 v[34:35], v[30:31], v[34:35], s[72:73] op_sel_hi:[1,1,0]
	v_pk_fma_f32 v[26:27], v[18:19], v[120:121], v[26:27]
	v_pk_fma_f32 v[34:35], v[30:31], v[34:35], s[74:75] op_sel_hi:[1,1,0]
	v_pk_fma_f32 v[20:21], v[20:21], v[112:113], v[124:125]
	v_pk_fma_f32 v[34:35], v[30:31], v[34:35], 1.0 op_sel_hi:[1,1,0]
	v_pk_fma_f32 v[30:31], v[30:31], v[32:33], s[58:59] op_sel_hi:[1,1,0]
	v_rcp_f32_e32 v34, v34
	v_rcp_f32_e32 v35, v35
	v_pk_mul_f32 v[28:29], v[28:29], v[30:31]
	v_pk_fma_f32 v[20:21], v[18:19], v[116:117], v[20:21]
	v_pk_fma_f32 v[18:19], v[18:19], v[112:113], v[124:125]
	v_pk_mul_f32 v[28:29], v[28:29], v[34:35]
	v_pk_fma_f32 v[20:21], v[10:11], v[120:121], v[20:21]
	v_pk_fma_f32 v[24:25], v[24:25], v[28:29], v[24:25]
	v_pk_fma_f32 v[18:19], v[10:11], v[116:117], v[18:19]
	v_pk_mul_f32 v[24:25], v[26:27], v[24:25]
	v_pk_fma_f32 v[18:19], v[2:3], v[120:121], v[18:19]
	v_cvt_pk_bf16_f32 v83, v24, v25
	v_pk_mul_f32 v[24:25], v[16:17], s[48:49] op_sel_hi:[1,0]
	v_pk_mul_f32 v[16:17], v[16:17], 0.5 op_sel_hi:[1,0]
	v_med3_f32 v24, v24, s97, v211
	v_med3_f32 v25, v25, s97, v211
	v_pk_mul_f32 v[26:27], v[24:25], v[24:25]
	v_pk_fma_f32 v[10:11], v[10:11], v[112:113], v[124:125]
	v_pk_fma_f32 v[30:31], v[26:27], s[60:61], v[114:115] op_sel_hi:[1,0,0] neg_lo:[1,0,0] neg_hi:[1,0,0]
	v_pk_fma_f32 v[28:29], v[26:27], s[52:53], v[106:107] op_sel_hi:[1,0,0]
	v_pk_fma_f32 v[30:31], v[26:27], v[30:31], s[62:63] op_sel_hi:[1,1,0]
	v_pk_fma_f32 v[28:29], v[26:27], v[28:29], s[54:55] op_sel_hi:[1,1,0]
	v_pk_fma_f32 v[30:31], v[26:27], v[30:31], s[66:67] op_sel_hi:[1,1,0]
	v_pk_fma_f32 v[28:29], v[26:27], v[28:29], s[56:57] op_sel_hi:[1,1,0]
	v_pk_fma_f32 v[30:31], v[26:27], v[30:31], s[72:73] op_sel_hi:[1,1,0]
	v_pk_fma_f32 v[10:11], v[2:3], v[116:117], v[10:11]
	v_pk_fma_f32 v[30:31], v[26:27], v[30:31], s[74:75] op_sel_hi:[1,1,0]
	v_pk_fma_f32 v[2:3], v[2:3], v[112:113], v[124:125]
	v_pk_fma_f32 v[30:31], v[26:27], v[30:31], 1.0 op_sel_hi:[1,1,0]
	v_pk_fma_f32 v[26:27], v[26:27], v[28:29], s[58:59] op_sel_hi:[1,1,0]
	v_rcp_f32_e32 v30, v30
	v_rcp_f32_e32 v31, v31
	v_pk_mul_f32 v[24:25], v[24:25], v[26:27]
	v_pk_fma_f32 v[10:11], v[4:5], v[120:121], v[10:11]
	v_pk_fma_f32 v[2:3], v[4:5], v[116:117], v[2:3]
	v_pk_mul_f32 v[24:25], v[24:25], v[30:31]
	s_cmp_eq_u32 s77, 0
	v_pk_fma_f32 v[16:17], v[16:17], v[24:25], v[16:17]
	s_cselect_b64 s[0:1], -1, 0
	v_pk_mul_f32 v[16:17], v[20:21], v[16:17]
	v_pk_fma_f32 v[2:3], v[120:121], v[12:13], v[2:3]
	v_cvt_pk_bf16_f32 v75, v16, v17
	v_pk_fma_f32 v[16:17], v[22:23], v[86:87], v[96:97]
	s_or_b64 s[12:13], s[64:65], s[0:1]
	v_pk_fma_f32 v[16:17], v[14:15], v[104:105], v[16:17]
	v_pk_fma_f32 v[14:15], v[14:15], v[86:87], v[96:97]
	v_pk_fma_f32 v[16:17], v[6:7], v[108:109], v[16:17]
	v_pk_fma_f32 v[14:15], v[6:7], v[104:105], v[14:15]
	v_pk_mul_f32 v[20:21], v[16:17], s[48:49] op_sel_hi:[1,0]
	v_pk_mul_f32 v[16:17], v[16:17], 0.5 op_sel_hi:[1,0]
	v_med3_f32 v20, v20, s97, v211
	v_med3_f32 v21, v21, s97, v211
	v_pk_mul_f32 v[22:23], v[20:21], v[20:21]
	v_pk_fma_f32 v[14:15], v[0:1], v[108:109], v[14:15]
	v_pk_fma_f32 v[26:27], v[22:23], s[60:61], v[114:115] op_sel_hi:[1,0,0] neg_lo:[1,0,0] neg_hi:[1,0,0]
	v_pk_fma_f32 v[24:25], v[22:23], s[52:53], v[106:107] op_sel_hi:[1,0,0]
	v_pk_fma_f32 v[26:27], v[22:23], v[26:27], s[62:63] op_sel_hi:[1,1,0]
	v_pk_fma_f32 v[24:25], v[22:23], v[24:25], s[54:55] op_sel_hi:[1,1,0]
	v_pk_fma_f32 v[26:27], v[22:23], v[26:27], s[66:67] op_sel_hi:[1,1,0]
	v_pk_fma_f32 v[24:25], v[22:23], v[24:25], s[56:57] op_sel_hi:[1,1,0]
	v_pk_fma_f32 v[26:27], v[22:23], v[26:27], s[72:73] op_sel_hi:[1,1,0]
	v_pk_fma_f32 v[6:7], v[6:7], v[86:87], v[96:97]
	v_pk_fma_f32 v[26:27], v[22:23], v[26:27], s[74:75] op_sel_hi:[1,1,0]
	v_pk_fma_f32 v[0:1], v[0:1], v[104:105], v[6:7]
	v_pk_fma_f32 v[26:27], v[22:23], v[26:27], 1.0 op_sel_hi:[1,1,0]
	v_pk_fma_f32 v[22:23], v[22:23], v[24:25], s[58:59] op_sel_hi:[1,1,0]
	v_rcp_f32_e32 v26, v26
	v_rcp_f32_e32 v27, v27
	v_pk_mul_f32 v[20:21], v[20:21], v[22:23]
	v_pk_fma_f32 v[0:1], v[108:109], v[8:9], v[0:1]
	v_pk_mul_f32 v[20:21], v[20:21], v[26:27]
	s_nop 0
	v_pk_fma_f32 v[16:17], v[16:17], v[20:21], v[16:17]
	v_pk_mul_f32 v[4:5], v[0:1], s[48:49] op_sel_hi:[1,0]
	v_pk_mul_f32 v[16:17], v[18:19], v[16:17]
	v_med3_f32 v4, v4, s97, v211
	v_cvt_pk_bf16_f32 v67, v16, v17
	v_pk_mul_f32 v[16:17], v[14:15], s[48:49] op_sel_hi:[1,0]
	v_pk_mul_f32 v[14:15], v[14:15], 0.5 op_sel_hi:[1,0]
	v_med3_f32 v16, v16, s97, v211
	v_med3_f32 v17, v17, s97, v211
	v_pk_mul_f32 v[18:19], v[16:17], v[16:17]
	v_med3_f32 v5, v5, s97, v211
	v_pk_fma_f32 v[22:23], v[18:19], s[60:61], v[114:115] op_sel_hi:[1,0,0] neg_lo:[1,0,0] neg_hi:[1,0,0]
	v_pk_fma_f32 v[20:21], v[18:19], s[52:53], v[106:107] op_sel_hi:[1,0,0]
	v_pk_fma_f32 v[22:23], v[18:19], v[22:23], s[62:63] op_sel_hi:[1,1,0]
	v_pk_fma_f32 v[20:21], v[18:19], v[20:21], s[54:55] op_sel_hi:[1,1,0]
	v_pk_fma_f32 v[22:23], v[18:19], v[22:23], s[66:67] op_sel_hi:[1,1,0]
	v_pk_fma_f32 v[20:21], v[18:19], v[20:21], s[56:57] op_sel_hi:[1,1,0]
	v_pk_fma_f32 v[22:23], v[18:19], v[22:23], s[72:73] op_sel_hi:[1,1,0]
	v_pk_mul_f32 v[6:7], v[4:5], v[4:5]
	v_pk_fma_f32 v[22:23], v[18:19], v[22:23], s[74:75] op_sel_hi:[1,1,0]
	v_pk_fma_f32 v[8:9], v[6:7], s[52:53], v[106:107] op_sel_hi:[1,0,0]
	v_pk_fma_f32 v[22:23], v[18:19], v[22:23], 1.0 op_sel_hi:[1,1,0]
	v_pk_fma_f32 v[18:19], v[18:19], v[20:21], s[58:59] op_sel_hi:[1,1,0]
	v_rcp_f32_e32 v22, v22
	v_rcp_f32_e32 v23, v23
	v_pk_mul_f32 v[16:17], v[16:17], v[18:19]
	v_pk_fma_f32 v[8:9], v[6:7], v[8:9], s[54:55] op_sel_hi:[1,1,0]
	v_pk_mul_f32 v[0:1], v[0:1], 0.5 op_sel_hi:[1,0]
	v_pk_mul_f32 v[16:17], v[16:17], v[22:23]
	v_pk_fma_f32 v[8:9], v[6:7], v[8:9], s[56:57] op_sel_hi:[1,1,0]
	v_pk_fma_f32 v[14:15], v[14:15], v[16:17], v[14:15]
	s_nop 0
	v_pk_mul_f32 v[10:11], v[10:11], v[14:15]
	s_nop 0
	v_cvt_pk_bf16_f32 v71, v10, v11
	v_pk_fma_f32 v[10:11], v[6:7], s[60:61], v[114:115] op_sel_hi:[1,0,0] neg_lo:[1,0,0] neg_hi:[1,0,0]
	s_nop 0
	v_pk_fma_f32 v[10:11], v[6:7], v[10:11], s[62:63] op_sel_hi:[1,1,0]
	s_nop 0
	v_pk_fma_f32 v[10:11], v[6:7], v[10:11], s[66:67] op_sel_hi:[1,1,0]
	s_nop 0
	v_pk_fma_f32 v[10:11], v[6:7], v[10:11], s[72:73] op_sel_hi:[1,1,0]
	s_nop 0
	v_pk_fma_f32 v[10:11], v[6:7], v[10:11], s[74:75] op_sel_hi:[1,1,0]
	s_nop 0
	v_pk_fma_f32 v[10:11], v[6:7], v[10:11], 1.0 op_sel_hi:[1,1,0]
	v_pk_fma_f32 v[6:7], v[6:7], v[8:9], s[58:59] op_sel_hi:[1,1,0]
	v_rcp_f32_e32 v10, v10
	v_rcp_f32_e32 v11, v11
	v_pk_mul_f32 v[4:5], v[4:5], v[6:7]
	s_nop 0
	v_pk_mul_f32 v[4:5], v[4:5], v[10:11]
	s_nop 0
	v_pk_fma_f32 v[0:1], v[0:1], v[4:5], v[0:1]
	s_nop 0
	v_pk_mul_f32 v[0:1], v[2:3], v[0:1]
	s_nop 0
	v_cvt_pk_bf16_f32 v79, v0, v1
	s_and_saveexec_b64 s[0:1], s[12:13]
	s_cbranch_execz .LBB0_570
	v_mov_b64_e32 v[0:1], s[28:29]
	v_mad_i64_i32 v[0:1], s[12:13], v174, s34, v[0:1]
	v_lshl_add_u64 v[0:1], v[176:177], 1, v[0:1]
	global_store_dwordx4 v[0:1], v[92:95], off

.LBB0_665:
	v_lshl_add_u32 v146, s63, 8, v148
	v_lshl_or_b32 v144, s3, 8, v150
	v_lshlrev_b32_e32 v145, 1, v144
	v_lshl_add_u32 v228, v146, 11, v145
	v_add_u32_e32 v229, 0x8000, v228
	v_add_u32_e32 v230, 0x10000, v228
	v_add_u32_e32 v231, 0x18000, v228
	v_add_u32_e32 v232, 0x40000, v228
	v_add_u32_e32 v233, 0x48000, v228
	v_add_u32_e32 v234, 0x50000, v228
	v_add_u32_e32 v235, 0x58000, v228
	global_load_dwordx4 v[156:159], v228, s[20:21]
	global_load_dwordx4 v[160:163], v228, s[20:21] offset:256
	global_load_dwordx4 v[164:167], v229, s[20:21]
	global_load_dwordx4 v[168:171], v229, s[20:21] offset:256
	global_load_dwordx4 v[172:175], v230, s[20:21]
	global_load_dwordx4 v[176:179], v230, s[20:21] offset:256
	global_load_dwordx4 v[180:183], v231, s[20:21]
	global_load_dwordx4 v[184:187], v231, s[20:21] offset:256
	global_load_dwordx4 v[188:191], v232, s[20:21]
	global_load_dwordx4 v[192:195], v232, s[20:21] offset:256
	global_load_dwordx4 v[196:199], v233, s[20:21]
	global_load_dwordx4 v[200:203], v233, s[20:21] offset:256
	global_load_dwordx4 v[204:207], v234, s[20:21]
	global_load_dwordx4 v[208:211], v234, s[20:21] offset:256
	global_load_dwordx4 v[212:215], v235, s[20:21]
	global_load_dwordx4 v[224:227], v235, s[20:21] offset:256
	s_and_b64 vcc, exec, s[38:39]
	s_cbranch_vccz .Lp6ep_nobar
	s_barrier
.Lp6ep_nobar:
	s_waitcnt vmcnt(15)
	v_lshlrev_b32_e32 v244, 16, v156
	v_and_b32_e32 v245, 0xffff0000, v156
	v_lshlrev_b32_e32 v246, 16, v157
	v_and_b32_e32 v247, 0xffff0000, v157
	v_lshlrev_b32_e32 v250, 16, v158
	v_and_b32_e32 v251, 0xffff0000, v158
	v_lshlrev_b32_e32 v252, 16, v159
	v_and_b32_e32 v253, 0xffff0000, v159
	v_pk_add_f32 v[124:125], v[124:125], v[244:245]
	v_pk_add_f32 v[126:127], v[126:127], v[246:247]
	v_pk_add_f32 v[120:121], v[120:121], v[250:251]
	v_pk_add_f32 v[122:123], v[122:123], v[252:253]
	v_pk_mul_f32 v[254:255], v[124:125], v[124:125]
	v_pk_fma_f32 v[254:255], v[126:127], v[126:127], v[254:255]
	v_pk_fma_f32 v[254:255], v[120:121], v[120:121], v[254:255]
	v_pk_fma_f32 v[254:255], v[122:123], v[122:123], v[254:255]
	v_cvt_pk_bf16_f32 v124, v124, v125
	v_cvt_pk_bf16_f32 v125, v126, v127
	v_cvt_pk_bf16_f32 v126, v120, v121
	v_cvt_pk_bf16_f32 v127, v122, v123
	global_store_dwordx4 v228, v[124:127], s[20:21]
	s_waitcnt vmcnt(15)
	v_lshlrev_b32_e32 v244, 16, v160
	v_and_b32_e32 v245, 0xffff0000, v160
	v_lshlrev_b32_e32 v246, 16, v161
	v_and_b32_e32 v247, 0xffff0000, v161
	v_lshlrev_b32_e32 v250, 16, v162
	v_and_b32_e32 v251, 0xffff0000, v162
	v_lshlrev_b32_e32 v252, 16, v163
	v_and_b32_e32 v253, 0xffff0000, v163
	v_pk_add_f32 v[116:117], v[116:117], v[244:245]
	v_pk_add_f32 v[118:119], v[118:119], v[246:247]
	v_pk_add_f32 v[112:113], v[112:113], v[250:251]
	v_pk_add_f32 v[114:115], v[114:115], v[252:253]
	v_pk_fma_f32 v[254:255], v[116:117], v[116:117], v[254:255]
	v_pk_fma_f32 v[254:255], v[118:119], v[118:119], v[254:255]
	v_pk_fma_f32 v[254:255], v[112:113], v[112:113], v[254:255]
	v_pk_fma_f32 v[254:255], v[114:115], v[114:115], v[254:255]
	v_cvt_pk_bf16_f32 v116, v116, v117
	v_cvt_pk_bf16_f32 v117, v118, v119
	v_cvt_pk_bf16_f32 v118, v112, v113
	v_cvt_pk_bf16_f32 v119, v114, v115
	global_store_dwordx4 v228, v[116:119], s[20:21] offset:256
	v_add_f32_e32 v112, v254, v255
	s_waitcnt vmcnt(15)
	v_lshlrev_b32_e32 v244, 16, v164
	v_and_b32_e32 v245, 0xffff0000, v164
	v_lshlrev_b32_e32 v246, 16, v165
	v_and_b32_e32 v247, 0xffff0000, v165
	v_lshlrev_b32_e32 v250, 16, v166
	v_and_b32_e32 v251, 0xffff0000, v166
	v_lshlrev_b32_e32 v252, 16, v167
	v_and_b32_e32 v253, 0xffff0000, v167
	v_pk_add_f32 v[108:109], v[108:109], v[244:245]
	v_pk_add_f32 v[110:111], v[110:111], v[246:247]
	v_pk_add_f32 v[104:105], v[104:105], v[250:251]
	v_pk_add_f32 v[106:107], v[106:107], v[252:253]
	v_pk_mul_f32 v[254:255], v[108:109], v[108:109]
	v_pk_fma_f32 v[254:255], v[110:111], v[110:111], v[254:255]
	v_pk_fma_f32 v[254:255], v[104:105], v[104:105], v[254:255]
	v_pk_fma_f32 v[254:255], v[106:107], v[106:107], v[254:255]
	v_cvt_pk_bf16_f32 v108, v108, v109
	v_cvt_pk_bf16_f32 v109, v110, v111
	v_cvt_pk_bf16_f32 v110, v104, v105
	v_cvt_pk_bf16_f32 v111, v106, v107
	global_store_dwordx4 v229, v[108:111], s[20:21]
	s_waitcnt vmcnt(15)
	v_lshlrev_b32_e32 v244, 16, v168
	v_and_b32_e32 v245, 0xffff0000, v168
	v_lshlrev_b32_e32 v246, 16, v169
	v_and_b32_e32 v247, 0xffff0000, v169
	v_lshlrev_b32_e32 v250, 16, v170
	v_and_b32_e32 v251, 0xffff0000, v170
	v_lshlrev_b32_e32 v252, 16, v171
	v_and_b32_e32 v253, 0xffff0000, v171
	v_pk_add_f32 v[100:101], v[100:101], v[244:245]
	v_pk_add_f32 v[102:103], v[102:103], v[246:247]
	v_pk_add_f32 v[96:97], v[96:97], v[250:251]
	v_pk_add_f32 v[98:99], v[98:99], v[252:253]
	v_pk_fma_f32 v[254:255], v[100:101], v[100:101], v[254:255]
	v_pk_fma_f32 v[254:255], v[102:103], v[102:103], v[254:255]
	v_pk_fma_f32 v[254:255], v[96:97], v[96:97], v[254:255]
	v_pk_fma_f32 v[254:255], v[98:99], v[98:99], v[254:255]
	v_cvt_pk_bf16_f32 v100, v100, v101
	v_cvt_pk_bf16_f32 v101, v102, v103
	v_cvt_pk_bf16_f32 v102, v96, v97
	v_cvt_pk_bf16_f32 v103, v98, v99
	global_store_dwordx4 v229, v[100:103], s[20:21] offset:256
	v_add_f32_e32 v96, v254, v255
	s_waitcnt vmcnt(15)
	v_lshlrev_b32_e32 v244, 16, v172
	v_and_b32_e32 v245, 0xffff0000, v172
	v_lshlrev_b32_e32 v246, 16, v173
	v_and_b32_e32 v247, 0xffff0000, v173
	v_lshlrev_b32_e32 v250, 16, v174
	v_and_b32_e32 v251, 0xffff0000, v174
	v_lshlrev_b32_e32 v252, 16, v175
	v_and_b32_e32 v253, 0xffff0000, v175
	v_pk_add_f32 v[92:93], v[92:93], v[244:245]
	v_pk_add_f32 v[94:95], v[94:95], v[246:247]
	v_pk_add_f32 v[88:89], v[88:89], v[250:251]
	v_pk_add_f32 v[90:91], v[90:91], v[252:253]
	v_pk_mul_f32 v[254:255], v[92:93], v[92:93]
	v_pk_fma_f32 v[254:255], v[94:95], v[94:95], v[254:255]
	v_pk_fma_f32 v[254:255], v[88:89], v[88:89], v[254:255]
	v_pk_fma_f32 v[254:255], v[90:91], v[90:91], v[254:255]
	v_cvt_pk_bf16_f32 v92, v92, v93
	v_cvt_pk_bf16_f32 v93, v94, v95
	v_cvt_pk_bf16_f32 v94, v88, v89
	v_cvt_pk_bf16_f32 v95, v90, v91
	global_store_dwordx4 v230, v[92:95], s[20:21]
	s_waitcnt vmcnt(15)
	v_lshlrev_b32_e32 v244, 16, v176
	v_and_b32_e32 v245, 0xffff0000, v176
	v_lshlrev_b32_e32 v246, 16, v177
	v_and_b32_e32 v247, 0xffff0000, v177
	v_lshlrev_b32_e32 v250, 16, v178
	v_and_b32_e32 v251, 0xffff0000, v178
	v_lshlrev_b32_e32 v252, 16, v179
	v_and_b32_e32 v253, 0xffff0000, v179
	v_pk_add_f32 v[84:85], v[84:85], v[244:245]
	v_pk_add_f32 v[86:87], v[86:87], v[246:247]
	v_pk_add_f32 v[80:81], v[80:81], v[250:251]
	v_pk_add_f32 v[82:83], v[82:83], v[252:253]
	v_pk_fma_f32 v[254:255], v[84:85], v[84:85], v[254:255]
	v_pk_fma_f32 v[254:255], v[86:87], v[86:87], v[254:255]
	v_pk_fma_f32 v[254:255], v[80:81], v[80:81], v[254:255]
	v_pk_fma_f32 v[254:255], v[82:83], v[82:83], v[254:255]
	v_cvt_pk_bf16_f32 v84, v84, v85
	v_cvt_pk_bf16_f32 v85, v86, v87
	v_cvt_pk_bf16_f32 v86, v80, v81
	v_cvt_pk_bf16_f32 v87, v82, v83
	global_store_dwordx4 v230, v[84:87], s[20:21] offset:256
	v_add_f32_e32 v80, v254, v255
	s_waitcnt vmcnt(15)
	v_lshlrev_b32_e32 v244, 16, v180
	v_and_b32_e32 v245, 0xffff0000, v180
	v_lshlrev_b32_e32 v246, 16, v181
	v_and_b32_e32 v247, 0xffff0000, v181
	v_lshlrev_b32_e32 v250, 16, v182
	v_and_b32_e32 v251, 0xffff0000, v182
	v_lshlrev_b32_e32 v252, 16, v183
	v_and_b32_e32 v253, 0xffff0000, v183
	v_pk_add_f32 v[76:77], v[76:77], v[244:245]
	v_pk_add_f32 v[78:79], v[78:79], v[246:247]
	v_pk_add_f32 v[72:73], v[72:73], v[250:251]
	v_pk_add_f32 v[74:75], v[74:75], v[252:253]
	v_pk_mul_f32 v[254:255], v[76:77], v[76:77]
	v_pk_fma_f32 v[254:255], v[78:79], v[78:79], v[254:255]
	v_pk_fma_f32 v[254:255], v[72:73], v[72:73], v[254:255]
	v_pk_fma_f32 v[254:255], v[74:75], v[74:75], v[254:255]
	v_cvt_pk_bf16_f32 v76, v76, v77
	v_cvt_pk_bf16_f32 v77, v78, v79
	v_cvt_pk_bf16_f32 v78, v72, v73
	v_cvt_pk_bf16_f32 v79, v74, v75
	global_store_dwordx4 v231, v[76:79], s[20:21]
	s_waitcnt vmcnt(15)
	v_lshlrev_b32_e32 v244, 16, v184
	v_and_b32_e32 v245, 0xffff0000, v184
	v_lshlrev_b32_e32 v246, 16, v185
	v_and_b32_e32 v247, 0xffff0000, v185
	v_lshlrev_b32_e32 v250, 16, v186
	v_and_b32_e32 v251, 0xffff0000, v186
	v_lshlrev_b32_e32 v252, 16, v187
	v_and_b32_e32 v253, 0xffff0000, v187
	v_pk_add_f32 v[68:69], v[68:69], v[244:245]
	v_pk_add_f32 v[70:71], v[70:71], v[246:247]
	v_pk_add_f32 v[64:65], v[64:65], v[250:251]
	v_pk_add_f32 v[66:67], v[66:67], v[252:253]
	v_pk_fma_f32 v[254:255], v[68:69], v[68:69], v[254:255]
	v_pk_fma_f32 v[254:255], v[70:71], v[70:71], v[254:255]
	v_pk_fma_f32 v[254:255], v[64:65], v[64:65], v[254:255]
	v_pk_fma_f32 v[254:255], v[66:67], v[66:67], v[254:255]
	v_cvt_pk_bf16_f32 v68, v68, v69
	v_cvt_pk_bf16_f32 v69, v70, v71
	v_cvt_pk_bf16_f32 v70, v64, v65
	v_cvt_pk_bf16_f32 v71, v66, v67
	global_store_dwordx4 v231, v[68:71], s[20:21] offset:256
	v_add_f32_e32 v64, v254, v255
	s_waitcnt vmcnt(15)
	v_lshlrev_b32_e32 v244, 16, v188
	v_and_b32_e32 v245, 0xffff0000, v188
	v_lshlrev_b32_e32 v246, 16, v189
	v_and_b32_e32 v247, 0xffff0000, v189
	v_lshlrev_b32_e32 v250, 16, v190
	v_and_b32_e32 v251, 0xffff0000, v190
	v_lshlrev_b32_e32 v252, 16, v191
	v_and_b32_e32 v253, 0xffff0000, v191
	v_pk_add_f32 v[60:61], v[60:61], v[244:245]
	v_pk_add_f32 v[62:63], v[62:63], v[246:247]
	v_pk_add_f32 v[56:57], v[56:57], v[250:251]
	v_pk_add_f32 v[58:59], v[58:59], v[252:253]
	v_pk_mul_f32 v[254:255], v[60:61], v[60:61]
	v_pk_fma_f32 v[254:255], v[62:63], v[62:63], v[254:255]
	v_pk_fma_f32 v[254:255], v[56:57], v[56:57], v[254:255]
	v_pk_fma_f32 v[254:255], v[58:59], v[58:59], v[254:255]
	v_cvt_pk_bf16_f32 v60, v60, v61
	v_cvt_pk_bf16_f32 v61, v62, v63
	v_cvt_pk_bf16_f32 v62, v56, v57
	v_cvt_pk_bf16_f32 v63, v58, v59
	global_store_dwordx4 v232, v[60:63], s[20:21]
	s_waitcnt vmcnt(15)
	v_lshlrev_b32_e32 v244, 16, v192
	v_and_b32_e32 v245, 0xffff0000, v192
	v_lshlrev_b32_e32 v246, 16, v193
	v_and_b32_e32 v247, 0xffff0000, v193
	v_lshlrev_b32_e32 v250, 16, v194
	v_and_b32_e32 v251, 0xffff0000, v194
	v_lshlrev_b32_e32 v252, 16, v195
	v_and_b32_e32 v253, 0xffff0000, v195
	v_pk_add_f32 v[52:53], v[52:53], v[244:245]
	v_pk_add_f32 v[54:55], v[54:55], v[246:247]
	v_pk_add_f32 v[48:49], v[48:49], v[250:251]
	v_pk_add_f32 v[50:51], v[50:51], v[252:253]
	v_pk_fma_f32 v[254:255], v[52:53], v[52:53], v[254:255]
	v_pk_fma_f32 v[254:255], v[54:55], v[54:55], v[254:255]
	v_pk_fma_f32 v[254:255], v[48:49], v[48:49], v[254:255]
	v_pk_fma_f32 v[254:255], v[50:51], v[50:51], v[254:255]
	v_cvt_pk_bf16_f32 v52, v52, v53
	v_cvt_pk_bf16_f32 v53, v54, v55
	v_cvt_pk_bf16_f32 v54, v48, v49
	v_cvt_pk_bf16_f32 v55, v50, v51
	global_store_dwordx4 v232, v[52:55], s[20:21] offset:256
	v_add_f32_e32 v48, v254, v255
	s_waitcnt vmcnt(15)
	v_lshlrev_b32_e32 v244, 16, v196
	v_and_b32_e32 v245, 0xffff0000, v196
	v_lshlrev_b32_e32 v246, 16, v197
	v_and_b32_e32 v247, 0xffff0000, v197
	v_lshlrev_b32_e32 v250, 16, v198
	v_and_b32_e32 v251, 0xffff0000, v198
	v_lshlrev_b32_e32 v252, 16, v199
	v_and_b32_e32 v253, 0xffff0000, v199
	v_pk_add_f32 v[44:45], v[44:45], v[244:245]
	v_pk_add_f32 v[46:47], v[46:47], v[246:247]
	v_pk_add_f32 v[40:41], v[40:41], v[250:251]
	v_pk_add_f32 v[42:43], v[42:43], v[252:253]
	v_pk_mul_f32 v[254:255], v[44:45], v[44:45]
	v_pk_fma_f32 v[254:255], v[46:47], v[46:47], v[254:255]
	v_pk_fma_f32 v[254:255], v[40:41], v[40:41], v[254:255]
	v_pk_fma_f32 v[254:255], v[42:43], v[42:43], v[254:255]
	v_cvt_pk_bf16_f32 v44, v44, v45
	v_cvt_pk_bf16_f32 v45, v46, v47
	v_cvt_pk_bf16_f32 v46, v40, v41
	v_cvt_pk_bf16_f32 v47, v42, v43
	global_store_dwordx4 v233, v[44:47], s[20:21]
	s_waitcnt vmcnt(15)
	v_lshlrev_b32_e32 v244, 16, v200
	v_and_b32_e32 v245, 0xffff0000, v200
	v_lshlrev_b32_e32 v246, 16, v201
	v_and_b32_e32 v247, 0xffff0000, v201
	v_lshlrev_b32_e32 v250, 16, v202
	v_and_b32_e32 v251, 0xffff0000, v202
	v_lshlrev_b32_e32 v252, 16, v203
	v_and_b32_e32 v253, 0xffff0000, v203
	v_pk_add_f32 v[36:37], v[36:37], v[244:245]
	v_pk_add_f32 v[38:39], v[38:39], v[246:247]
	v_pk_add_f32 v[32:33], v[32:33], v[250:251]
	v_pk_add_f32 v[34:35], v[34:35], v[252:253]
	v_pk_fma_f32 v[254:255], v[36:37], v[36:37], v[254:255]
	v_pk_fma_f32 v[254:255], v[38:39], v[38:39], v[254:255]
	v_pk_fma_f32 v[254:255], v[32:33], v[32:33], v[254:255]
	v_pk_fma_f32 v[254:255], v[34:35], v[34:35], v[254:255]
	v_cvt_pk_bf16_f32 v36, v36, v37
	v_cvt_pk_bf16_f32 v37, v38, v39
	v_cvt_pk_bf16_f32 v38, v32, v33
	v_cvt_pk_bf16_f32 v39, v34, v35
	global_store_dwordx4 v233, v[36:39], s[20:21] offset:256
	v_add_f32_e32 v32, v254, v255
	s_waitcnt vmcnt(15)
	v_lshlrev_b32_e32 v244, 16, v204
	v_and_b32_e32 v245, 0xffff0000, v204
	v_lshlrev_b32_e32 v246, 16, v205
	v_and_b32_e32 v247, 0xffff0000, v205
	v_lshlrev_b32_e32 v250, 16, v206
	v_and_b32_e32 v251, 0xffff0000, v206
	v_lshlrev_b32_e32 v252, 16, v207
	v_and_b32_e32 v253, 0xffff0000, v207
	v_pk_add_f32 v[28:29], v[28:29], v[244:245]
	v_pk_add_f32 v[30:31], v[30:31], v[246:247]
	v_pk_add_f32 v[24:25], v[24:25], v[250:251]
	v_pk_add_f32 v[26:27], v[26:27], v[252:253]
	v_pk_mul_f32 v[254:255], v[28:29], v[28:29]
	v_pk_fma_f32 v[254:255], v[30:31], v[30:31], v[254:255]
	v_pk_fma_f32 v[254:255], v[24:25], v[24:25], v[254:255]
	v_pk_fma_f32 v[254:255], v[26:27], v[26:27], v[254:255]
	v_cvt_pk_bf16_f32 v28, v28, v29
	v_cvt_pk_bf16_f32 v29, v30, v31
	v_cvt_pk_bf16_f32 v30, v24, v25
	v_cvt_pk_bf16_f32 v31, v26, v27
	global_store_dwordx4 v234, v[28:31], s[20:21]
	s_waitcnt vmcnt(15)
	v_lshlrev_b32_e32 v244, 16, v208
	v_and_b32_e32 v245, 0xffff0000, v208
	v_lshlrev_b32_e32 v246, 16, v209
	v_and_b32_e32 v247, 0xffff0000, v209
	v_lshlrev_b32_e32 v250, 16, v210
	v_and_b32_e32 v251, 0xffff0000, v210
	v_lshlrev_b32_e32 v252, 16, v211
	v_and_b32_e32 v253, 0xffff0000, v211
	v_pk_add_f32 v[20:21], v[20:21], v[244:245]
	v_pk_add_f32 v[22:23], v[22:23], v[246:247]
	v_pk_add_f32 v[16:17], v[16:17], v[250:251]
	v_pk_add_f32 v[18:19], v[18:19], v[252:253]
	v_pk_fma_f32 v[254:255], v[20:21], v[20:21], v[254:255]
	v_pk_fma_f32 v[254:255], v[22:23], v[22:23], v[254:255]
	v_pk_fma_f32 v[254:255], v[16:17], v[16:17], v[254:255]
	v_pk_fma_f32 v[254:255], v[18:19], v[18:19], v[254:255]
	v_cvt_pk_bf16_f32 v20, v20, v21
	v_cvt_pk_bf16_f32 v21, v22, v23
	v_cvt_pk_bf16_f32 v22, v16, v17
	v_cvt_pk_bf16_f32 v23, v18, v19
	global_store_dwordx4 v234, v[20:23], s[20:21] offset:256
	v_add_f32_e32 v16, v254, v255
	s_waitcnt vmcnt(15)
	v_lshlrev_b32_e32 v244, 16, v212
	v_and_b32_e32 v245, 0xffff0000, v212
	v_lshlrev_b32_e32 v246, 16, v213
	v_and_b32_e32 v247, 0xffff0000, v213
	v_lshlrev_b32_e32 v250, 16, v214
	v_and_b32_e32 v251, 0xffff0000, v214
	v_lshlrev_b32_e32 v252, 16, v215
	v_and_b32_e32 v253, 0xffff0000, v215
	v_pk_add_f32 v[12:13], v[12:13], v[244:245]
	v_pk_add_f32 v[14:15], v[14:15], v[246:247]
	v_pk_add_f32 v[8:9], v[8:9], v[250:251]
	v_pk_add_f32 v[10:11], v[10:11], v[252:253]
	v_pk_mul_f32 v[254:255], v[12:13], v[12:13]
	v_pk_fma_f32 v[254:255], v[14:15], v[14:15], v[254:255]
	v_pk_fma_f32 v[254:255], v[8:9], v[8:9], v[254:255]
	v_pk_fma_f32 v[254:255], v[10:11], v[10:11], v[254:255]
	v_cvt_pk_bf16_f32 v12, v12, v13
	v_cvt_pk_bf16_f32 v13, v14, v15
	v_cvt_pk_bf16_f32 v14, v8, v9
	v_cvt_pk_bf16_f32 v15, v10, v11
	global_store_dwordx4 v235, v[12:15], s[20:21]
	s_waitcnt vmcnt(15)
	v_lshlrev_b32_e32 v244, 16, v224
	v_and_b32_e32 v245, 0xffff0000, v224
	v_lshlrev_b32_e32 v246, 16, v225
	v_and_b32_e32 v247, 0xffff0000, v225
	v_lshlrev_b32_e32 v250, 16, v226
	v_and_b32_e32 v251, 0xffff0000, v226
	v_lshlrev_b32_e32 v252, 16, v227
	v_and_b32_e32 v253, 0xffff0000, v227
	v_pk_add_f32 v[4:5], v[4:5], v[244:245]
	v_pk_add_f32 v[6:7], v[6:7], v[246:247]
	v_pk_add_f32 v[0:1], v[0:1], v[250:251]
	v_pk_add_f32 v[2:3], v[2:3], v[252:253]
	v_pk_fma_f32 v[254:255], v[4:5], v[4:5], v[254:255]
	v_pk_fma_f32 v[254:255], v[6:7], v[6:7], v[254:255]
	v_pk_fma_f32 v[254:255], v[0:1], v[0:1], v[254:255]
	v_pk_fma_f32 v[254:255], v[2:3], v[2:3], v[254:255]
	v_cvt_pk_bf16_f32 v4, v4, v5
	v_cvt_pk_bf16_f32 v5, v6, v7
	v_cvt_pk_bf16_f32 v6, v0, v1
	v_cvt_pk_bf16_f32 v7, v2, v3
	global_store_dwordx4 v235, v[4:7], s[20:21] offset:256
	v_add_f32_e32 v0, v254, v255
	v_xor_b32_e32 v244, 16, v154
	v_xor_b32_e32 v245, 32, v154
	v_lshlrev_b32_e32 v244, 2, v244
	v_lshlrev_b32_e32 v245, 2, v245
	ds_bpermute_b32 v156, v244, v112
	ds_bpermute_b32 v157, v244, v96
	ds_bpermute_b32 v158, v244, v80
	ds_bpermute_b32 v159, v244, v64
	ds_bpermute_b32 v160, v244, v48
	ds_bpermute_b32 v161, v244, v32
	ds_bpermute_b32 v162, v244, v16
	ds_bpermute_b32 v163, v244, v0
	s_waitcnt lgkmcnt(0)
	v_add_f32_e32 v112, v112, v156
	v_add_f32_e32 v96, v96, v157
	v_add_f32_e32 v80, v80, v158
	v_add_f32_e32 v64, v64, v159
	v_add_f32_e32 v48, v48, v160
	v_add_f32_e32 v32, v32, v161
	v_add_f32_e32 v16, v16, v162
	v_add_f32_e32 v0, v0, v163
	ds_bpermute_b32 v156, v245, v112
	ds_bpermute_b32 v157, v245, v96
	ds_bpermute_b32 v158, v245, v80
	ds_bpermute_b32 v159, v245, v64
	ds_bpermute_b32 v160, v245, v48
	ds_bpermute_b32 v161, v245, v32
	ds_bpermute_b32 v162, v245, v16
	ds_bpermute_b32 v163, v245, v0
	v_lshlrev_b32_e32 v145, 2, v146
	s_waitcnt lgkmcnt(0)
	v_add_f32_e32 v112, v112, v156
	v_add_f32_e32 v96, v96, v157
	v_add_f32_e32 v80, v80, v158
	v_add_f32_e32 v64, v64, v159
	v_add_f32_e32 v48, v48, v160
	v_add_f32_e32 v32, v32, v161
	v_add_f32_e32 v16, v16, v162
	v_add_f32_e32 v0, v0, v163
	s_and_saveexec_b64 s[42:43], s[6:7]
	s_cbranch_execz .Lepi_p6_noatom
	global_atomic_add_f32 v145, v112, s[22:23]
	global_atomic_add_f32 v145, v96, s[22:23] offset:64
	global_atomic_add_f32 v145, v80, s[22:23] offset:128
	global_atomic_add_f32 v145, v64, s[22:23] offset:192
	global_atomic_add_f32 v145, v48, s[22:23] offset:512
	global_atomic_add_f32 v145, v32, s[22:23] offset:576
	global_atomic_add_f32 v145, v16, s[22:23] offset:640
	global_atomic_add_f32 v145, v0, s[22:23] offset:704
